# GEMM K-loops: all s_setprio removed (both the block-level raise and the inner flip); everything else as v32
# speedup vs baseline: 1.0025x; 1.0025x over previous
; #define PG8_STAGE(bufoff, gbase, voff) do { _Pragma("unroll") for (int _i = 0; _i < 2; ++_i) \
;         __builtin_amdgcn_global_load_lds((const unsigned*)((const char*)(gbase) + (voff)[_i]), (PG8_LAS unsigned*)(lds + (bufoff) + ldsw + _i * 8192), 16, 0, 0); } while (0)
; #define PG8_LDA(dst, b, h) do { _Pragma("unroll") for (int m = 0; m < 4; ++m) _Pragma("unroll") for (int k = 0; k < 2; ++k) dst[m][k] = *(const PG8_LAS bf16x8*)(lds + PG8_SA(b, h) + aoff + m * 2048 + k * 1024); } while (0)
; #define PG8_LDB(dst, b, h) do { _Pragma("unroll") for (int n = 0; n < 2; ++n) _Pragma("unroll") for (int k = 0; k < 2; ++k) dst[n][k] = *(const PG8_LAS bf16x8*)(lds + PG8_SB(b, h) + boff + n * 2048 + k * 1024); } while (0)
; #define PG8_MMA(ai, bj, At, Bt) do { __builtin_amdgcn_s_setprio(1); _Pragma("unroll") for (int m = 0; m < 4; ++m) _Pragma("unroll") for (int n = 0; n < 2; ++n) _Pragma("unroll") for (int k = 0; k < 2; ++k) \
;         acc[ai][bj][m][n] = __builtin_amdgcn_mfma_f32_16x16x32_bf16(Bt[n][k], At[m][k], acc[ai][bj][m][n], 0, 0, 0); __builtin_amdgcn_s_setprio(0); } while (0)
; #define PG8_WAIT_V(n) asm volatile("s_waitcnt vmcnt(" #n ")" ::: "memory")
; #define PG8_WAIT_L(n) asm volatile("s_waitcnt lgkmcnt(" #n ")" ::: "memory")
; template <class Epi, class Sched, bool ALIGN_EPI = false, bool SP2 = false>
; __device__ __forceinline__ void gemm_phase(PG8_LAS unsigned char* lds, const Gemm g, const Sched& S, const Epi& E) {
;     ...
;             const bool last = (t == nt - 2);
;             const char* a1 = cA + (size_t)(t + 1) * kstep;
;             const char* a2 = last ? nA : cA + (size_t)(t + 2) * kstep; const char* b2 = last ? nB : cB + (size_t)(t + 2) * kstep;
;             const char* a3 = a2 + kstep; const char* b3 = b2 + kstep;
;             if (last && has_next) S.a_ready(nxt);
;             if constexpr (SP2) {
;             PG8_LDB(B0, 0, 0); PG8_LDB(B1, 0, 1); PG8_SCHED; PG8_LDA(At, 0, 0); PG8_STAGE(PG8_SA(1, 1), a1 + hstep, voffA);
;             PG8_WAIT_V(8); PG8_WAIT_L(0); PG8_BAR; PG8_MMA(0, 0, At, B0); PG8_MMA(0, 1, At, B1); PG8_BAR; PG8_SCHED;
;             PG8_LDA(At, 0, 1); PG8_STAGE(PG8_SB(0, 0), b2, voffB); PG8_STAGE(PG8_SB(0, 1), b2 + hstep, voffB); PG8_STAGE(PG8_SA(0, 0), a2, voffA);
;             PG8_WAIT_V(8); PG8_WAIT_L(0); PG8_BAR; PG8_MMA(1, 0, At, B0); PG8_MMA(1, 1, At, B1); PG8_BAR; PG8_SCHED;
.LBB0_119:
	ds_read_b128 v[154:157], v151
	ds_read_b128 v[158:161], v151 offset:1024
	ds_read_b128 v[162:165], v151 offset:2048
	ds_read_b128 v[166:169], v151 offset:3072
	ds_read_b128 v[170:173], v152
	ds_read_b128 v[174:177], v152 offset:1024
	ds_read_b128 v[178:181], v152 offset:2048
	ds_read_b128 v[182:185], v152 offset:3072
	s_add_u32 s70, s68, 0xfff80080
	s_addc_u32 s71, s69, -1
	s_cmp_eq_u32 s93, 28
	s_cselect_b32 s73, s35, s71
	s_cselect_b32 s72, s89, s70
	s_cselect_b32 s71, s21, s92
	s_cselect_b32 s70, s90, s91
	v_lshl_add_u64 v[218:219], s[68:69], 0, v[136:137]
	s_add_i32 m0, s19, 0xc000
	ds_read_b128 v[186:189], v153
	ds_read_b128 v[190:193], v153 offset:1024
	ds_read_b128 v[194:197], v153 offset:2048
	ds_read_b128 v[198:201], v153 offset:3072
	ds_read_b128 v[202:205], v153 offset:4096
	ds_read_b128 v[206:209], v153 offset:5120
	ds_read_b128 v[210:213], v153 offset:6144
	ds_read_b128 v[214:217], v153 offset:7168
	global_load_lds_dwordx4 v[218:219], off
	v_lshl_add_u64 v[218:219], s[68:69], 0, v[138:139]
	s_add_i32 m0, s19, 0xe000
	s_nop 0
	global_load_lds_dwordx4 v[218:219], off
	s_waitcnt vmcnt(8)
	s_waitcnt lgkmcnt(0)
	s_barrier
	s_waitcnt lgkmcnt(0)
	v_mfma_f32_16x16x32_bf16 v[124:127], v[154:157], v[186:189], v[124:127]
	v_mfma_f32_16x16x32_bf16 v[120:123], v[162:165], v[186:189], v[120:123]
	v_mfma_f32_16x16x32_bf16 v[116:119], v[154:157], v[194:197], v[116:119]
	v_mfma_f32_16x16x32_bf16 v[112:115], v[162:165], v[194:197], v[112:115]
	v_mfma_f32_16x16x32_bf16 v[100:103], v[154:157], v[202:205], v[100:103]
	v_mfma_f32_16x16x32_bf16 v[96:99], v[162:165], v[202:205], v[96:99]
	v_mfma_f32_16x16x32_bf16 v[84:87], v[154:157], v[210:213], v[84:87]
	v_mfma_f32_16x16x32_bf16 v[80:83], v[162:165], v[210:213], v[80:83]
	v_mfma_f32_16x16x32_bf16 v[124:127], v[158:161], v[190:193], v[124:127]
	v_mfma_f32_16x16x32_bf16 v[120:123], v[166:169], v[190:193], v[120:123]
	v_mfma_f32_16x16x32_bf16 v[116:119], v[158:161], v[198:201], v[116:119]
	v_mfma_f32_16x16x32_bf16 v[112:115], v[166:169], v[198:201], v[112:115]
	v_mfma_f32_16x16x32_bf16 v[100:103], v[158:161], v[206:209], v[100:103]
	v_mfma_f32_16x16x32_bf16 v[96:99], v[166:169], v[206:209], v[96:99]
	v_mfma_f32_16x16x32_bf16 v[84:87], v[158:161], v[214:217], v[84:87]
	v_mfma_f32_16x16x32_bf16 v[80:83], v[166:169], v[214:217], v[80:83]
	v_mfma_f32_16x16x32_bf16 v[108:111], v[170:173], v[186:189], v[108:111]
	v_mfma_f32_16x16x32_bf16 v[104:107], v[178:181], v[186:189], v[104:107]
	v_mfma_f32_16x16x32_bf16 v[92:95], v[170:173], v[194:197], v[92:95]
	v_mfma_f32_16x16x32_bf16 v[88:91], v[178:181], v[194:197], v[88:91]
	v_mfma_f32_16x16x32_bf16 v[76:79], v[170:173], v[202:205], v[76:79]
	v_mfma_f32_16x16x32_bf16 v[72:75], v[178:181], v[202:205], v[72:75]
	v_mfma_f32_16x16x32_bf16 v[68:71], v[170:173], v[210:213], v[68:71]
	v_mfma_f32_16x16x32_bf16 v[64:67], v[178:181], v[210:213], v[64:67]
	v_mfma_f32_16x16x32_bf16 v[108:111], v[174:177], v[190:193], v[108:111]
	v_mfma_f32_16x16x32_bf16 v[104:107], v[182:185], v[190:193], v[104:107]
	v_mfma_f32_16x16x32_bf16 v[92:95], v[174:177], v[198:201], v[92:95]
	v_mfma_f32_16x16x32_bf16 v[88:91], v[182:185], v[198:201], v[88:91]
	v_mfma_f32_16x16x32_bf16 v[76:79], v[174:177], v[206:209], v[76:79]
	v_mfma_f32_16x16x32_bf16 v[72:75], v[182:185], v[206:209], v[72:75]
	v_mfma_f32_16x16x32_bf16 v[68:71], v[174:177], v[214:217], v[68:71]
	v_mfma_f32_16x16x32_bf16 v[64:67], v[182:185], v[214:217], v[64:67]
	s_barrier
	s_add_i32 s94, s86, s55
	v_lshl_add_u64 v[218:219], s[70:71], 0, v[130:131]
	s_mov_b32 m0, s94
	ds_read_b128 v[186:189], v153 offset:16384
	ds_read_b128 v[190:193], v153 offset:17408
	ds_read_b128 v[194:197], v153 offset:18432
	ds_read_b128 v[198:201], v153 offset:19456
	ds_read_b128 v[202:205], v153 offset:20480
	ds_read_b128 v[206:209], v153 offset:21504
	ds_read_b128 v[210:213], v153 offset:22528
	ds_read_b128 v[214:217], v153 offset:23552
	global_load_lds_dwordx4 v[218:219], off
	s_add_i32 m0, s94, 0x2000
	s_add_u32 s94, s70, 0x80000
	v_lshl_add_u64 v[220:221], s[70:71], 0, v[134:135]
	s_addc_u32 s95, s71, 0
	s_add_i32 s96, s87, s55
	global_load_lds_dwordx4 v[220:221], off
	v_lshl_add_u64 v[222:223], s[94:95], 0, v[130:131]
	s_mov_b32 m0, s96
	v_lshl_add_u64 v[224:225], s[72:73], 0, v[132:133]
	global_load_lds_dwordx4 v[222:223], off
	v_lshl_add_u64 v[222:223], s[94:95], 0, v[134:135]
	s_add_i32 m0, s96, 0x2000
	s_nop 0
	global_load_lds_dwordx4 v[222:223], off
	v_lshl_add_u64 v[222:223], s[72:73], 0, v[128:129]
	s_mov_b32 m0, s19
	s_nop 0
	global_load_lds_dwordx4 v[222:223], off
	s_mov_b32 m0, s75
	s_nop 0
	global_load_lds_dwordx4 v[224:225], off
	s_waitcnt vmcnt(8)
	s_waitcnt lgkmcnt(0)
	s_barrier
; #define PG8_STAGE(bufoff, gbase, voff) do { _Pragma("unroll") for (int _i = 0; _i < 2; ++_i) \
;         __builtin_amdgcn_global_load_lds((const unsigned*)((const char*)(gbase) + (voff)[_i]), (PG8_LAS unsigned*)(lds + (bufoff) + ldsw + _i * 8192), 16, 0, 0); } while (0)
; #define PG8_LDA(dst, b, h) do { _Pragma("unroll") for (int m = 0; m < 4; ++m) _Pragma("unroll") for (int k = 0; k < 2; ++k) dst[m][k] = *(const PG8_LAS bf16x8*)(lds + PG8_SA(b, h) + aoff + m * 2048 + k * 1024); } while (0)
; #define PG8_LDB(dst, b, h) do { _Pragma("unroll") for (int n = 0; n < 2; ++n) _Pragma("unroll") for (int k = 0; k < 2; ++k) dst[n][k] = *(const PG8_LAS bf16x8*)(lds + PG8_SB(b, h) + boff + n * 2048 + k * 1024); } while (0)
; #define PG8_MMA(ai, bj, At, Bt) do { __builtin_amdgcn_s_setprio(1); _Pragma("unroll") for (int m = 0; m < 4; ++m) _Pragma("unroll") for (int n = 0; n < 2; ++n) _Pragma("unroll") for (int k = 0; k < 2; ++k) \
;         acc[ai][bj][m][n] = __builtin_amdgcn_mfma_f32_16x16x32_bf16(Bt[n][k], At[m][k], acc[ai][bj][m][n], 0, 0, 0); __builtin_amdgcn_s_setprio(0); } while (0)
; #define PG8_WAIT_V(n) asm volatile("s_waitcnt vmcnt(" #n ")" ::: "memory")
; #define PG8_WAIT_L(n) asm volatile("s_waitcnt lgkmcnt(" #n ")" ::: "memory")
; #define PG8_BAR __builtin_amdgcn_s_barrier()
; #define PG8_SCHED __builtin_amdgcn_sched_barrier(0)
; template <class Epi, class Sched, bool ALIGN_EPI = false, bool SP2 = false>
; __device__ __forceinline__ void gemm_phase(PG8_LAS unsigned char* lds, const Gemm g, const Sched& S, const Epi& E) {
;     ...
;             PG8_WAIT_V(8); PG8_WAIT_L(0); PG8_BAR; PG8_MMA(1, 0, At, B0); PG8_MMA(1, 1, At, B1); PG8_BAR; PG8_SCHED;
;             PG8_LDB(B0, 1, 0); PG8_LDB(B1, 1, 1); PG8_SCHED; PG8_LDA(At, 1, 0); PG8_STAGE(PG8_SA(0, 1), a2 + hstep, voffA);
;             PG8_WAIT_V(8); PG8_WAIT_L(0); PG8_BAR; PG8_MMA(0, 0, At, B0); PG8_MMA(0, 1, At, B1); PG8_BAR; PG8_SCHED;
	s_waitcnt lgkmcnt(0)
	v_mfma_f32_16x16x32_bf16 v[60:63], v[154:157], v[186:189], v[60:63]
	v_mfma_f32_16x16x32_bf16 v[56:59], v[162:165], v[186:189], v[56:59]
	v_mfma_f32_16x16x32_bf16 v[52:55], v[154:157], v[194:197], v[52:55]
	v_mfma_f32_16x16x32_bf16 v[48:51], v[162:165], v[194:197], v[48:51]
	v_mfma_f32_16x16x32_bf16 v[36:39], v[154:157], v[202:205], v[36:39]
	v_mfma_f32_16x16x32_bf16 v[32:35], v[162:165], v[202:205], v[32:35]
	v_mfma_f32_16x16x32_bf16 v[20:23], v[154:157], v[210:213], v[20:23]
	v_mfma_f32_16x16x32_bf16 v[16:19], v[162:165], v[210:213], v[16:19]
	v_mfma_f32_16x16x32_bf16 v[60:63], v[158:161], v[190:193], v[60:63]
	v_mfma_f32_16x16x32_bf16 v[56:59], v[166:169], v[190:193], v[56:59]
	v_mfma_f32_16x16x32_bf16 v[52:55], v[158:161], v[198:201], v[52:55]
	v_mfma_f32_16x16x32_bf16 v[48:51], v[166:169], v[198:201], v[48:51]
	v_mfma_f32_16x16x32_bf16 v[36:39], v[158:161], v[206:209], v[36:39]
	v_mfma_f32_16x16x32_bf16 v[32:35], v[166:169], v[206:209], v[32:35]
	v_mfma_f32_16x16x32_bf16 v[20:23], v[158:161], v[214:217], v[20:23]
	v_mfma_f32_16x16x32_bf16 v[16:19], v[166:169], v[214:217], v[16:19]
	v_mfma_f32_16x16x32_bf16 v[44:47], v[170:173], v[186:189], v[44:47]
	v_mfma_f32_16x16x32_bf16 v[40:43], v[178:181], v[186:189], v[40:43]
	v_mfma_f32_16x16x32_bf16 v[28:31], v[170:173], v[194:197], v[28:31]
	v_mfma_f32_16x16x32_bf16 v[24:27], v[178:181], v[194:197], v[24:27]
	v_mfma_f32_16x16x32_bf16 v[12:15], v[170:173], v[202:205], v[12:15]
	v_mfma_f32_16x16x32_bf16 v[8:11], v[178:181], v[202:205], v[8:11]
	v_mfma_f32_16x16x32_bf16 v[4:7], v[170:173], v[210:213], v[4:7]
	v_mfma_f32_16x16x32_bf16 v[0:3], v[178:181], v[210:213], v[0:3]
	v_mfma_f32_16x16x32_bf16 v[44:47], v[174:177], v[190:193], v[44:47]
	v_mfma_f32_16x16x32_bf16 v[40:43], v[182:185], v[190:193], v[40:43]
	v_mfma_f32_16x16x32_bf16 v[28:31], v[174:177], v[198:201], v[28:31]
	v_mfma_f32_16x16x32_bf16 v[24:27], v[182:185], v[198:201], v[24:27]
	v_mfma_f32_16x16x32_bf16 v[12:15], v[174:177], v[206:209], v[12:15]
	v_mfma_f32_16x16x32_bf16 v[8:11], v[182:185], v[206:209], v[8:11]
	v_mfma_f32_16x16x32_bf16 v[4:7], v[174:177], v[214:217], v[4:7]
	v_mfma_f32_16x16x32_bf16 v[0:3], v[182:185], v[214:217], v[0:3]
	s_barrier
	s_add_i32 s94, 0, 0x18000
	s_add_i32 s95, 0, 0x1c000
	v_add_u32_e32 v166, s94, v149
	v_add_u32_e32 v182, s95, v149
	ds_read_b128 v[154:157], v166
	ds_read_b128 v[158:161], v166 offset:1024
	ds_read_b128 v[162:165], v166 offset:2048
	ds_read_b128 v[166:169], v166 offset:3072
	ds_read_b128 v[170:173], v182
	ds_read_b128 v[174:177], v182 offset:1024
	ds_read_b128 v[178:181], v182 offset:2048
	ds_read_b128 v[182:185], v182 offset:3072
	s_add_u32 s72, s72, 0x80000
	s_addc_u32 s73, s73, 0
	s_mov_b32 m0, s76
	v_lshl_add_u64 v[226:227], s[72:73], 0, v[128:129]
	ds_read_b128 v[186:189], v153 offset:32768
	ds_read_b128 v[190:193], v153 offset:33792
	ds_read_b128 v[194:197], v153 offset:34816
	ds_read_b128 v[198:201], v153 offset:35840
	ds_read_b128 v[202:205], v153 offset:36864
	ds_read_b128 v[206:209], v153 offset:37888
	ds_read_b128 v[210:213], v153 offset:38912
	ds_read_b128 v[214:217], v153 offset:39936
	global_load_lds_dwordx4 v[226:227], off
	v_lshl_add_u64 v[226:227], s[72:73], 0, v[132:133]
	s_mov_b32 m0, s77
	s_nop 0
	global_load_lds_dwordx4 v[226:227], off
	s_waitcnt vmcnt(8)
	s_waitcnt lgkmcnt(0)
	s_barrier
	s_waitcnt lgkmcnt(0)
	v_mfma_f32_16x16x32_bf16 v[124:127], v[154:157], v[186:189], v[124:127]
	v_mfma_f32_16x16x32_bf16 v[120:123], v[162:165], v[186:189], v[120:123]
	v_mfma_f32_16x16x32_bf16 v[116:119], v[154:157], v[194:197], v[116:119]
	v_mfma_f32_16x16x32_bf16 v[112:115], v[162:165], v[194:197], v[112:115]
	v_mfma_f32_16x16x32_bf16 v[100:103], v[154:157], v[202:205], v[100:103]
	v_mfma_f32_16x16x32_bf16 v[96:99], v[162:165], v[202:205], v[96:99]
	v_mfma_f32_16x16x32_bf16 v[84:87], v[154:157], v[210:213], v[84:87]
	v_mfma_f32_16x16x32_bf16 v[80:83], v[162:165], v[210:213], v[80:83]
	v_mfma_f32_16x16x32_bf16 v[124:127], v[158:161], v[190:193], v[124:127]
	v_mfma_f32_16x16x32_bf16 v[120:123], v[166:169], v[190:193], v[120:123]
	v_mfma_f32_16x16x32_bf16 v[116:119], v[158:161], v[198:201], v[116:119]
	v_mfma_f32_16x16x32_bf16 v[112:115], v[166:169], v[198:201], v[112:115]
	v_mfma_f32_16x16x32_bf16 v[100:103], v[158:161], v[206:209], v[100:103]
	v_mfma_f32_16x16x32_bf16 v[96:99], v[166:169], v[206:209], v[96:99]
	v_mfma_f32_16x16x32_bf16 v[84:87], v[158:161], v[214:217], v[84:87]
	v_mfma_f32_16x16x32_bf16 v[80:83], v[166:169], v[214:217], v[80:83]
	v_mfma_f32_16x16x32_bf16 v[108:111], v[170:173], v[186:189], v[108:111]
	v_mfma_f32_16x16x32_bf16 v[104:107], v[178:181], v[186:189], v[104:107]
	v_mfma_f32_16x16x32_bf16 v[92:95], v[170:173], v[194:197], v[92:95]
	v_mfma_f32_16x16x32_bf16 v[88:91], v[178:181], v[194:197], v[88:91]
	v_mfma_f32_16x16x32_bf16 v[76:79], v[170:173], v[202:205], v[76:79]
	v_mfma_f32_16x16x32_bf16 v[72:75], v[178:181], v[202:205], v[72:75]
	v_mfma_f32_16x16x32_bf16 v[68:71], v[170:173], v[210:213], v[68:71]
	v_mfma_f32_16x16x32_bf16 v[64:67], v[178:181], v[210:213], v[64:67]
	v_mfma_f32_16x16x32_bf16 v[108:111], v[174:177], v[190:193], v[108:111]
	v_mfma_f32_16x16x32_bf16 v[104:107], v[182:185], v[190:193], v[104:107]
	v_mfma_f32_16x16x32_bf16 v[92:95], v[174:177], v[198:201], v[92:95]
	v_mfma_f32_16x16x32_bf16 v[88:91], v[182:185], v[198:201], v[88:91]
	v_mfma_f32_16x16x32_bf16 v[76:79], v[174:177], v[206:209], v[76:79]
	v_mfma_f32_16x16x32_bf16 v[72:75], v[182:185], v[206:209], v[72:75]
	v_mfma_f32_16x16x32_bf16 v[68:71], v[174:177], v[214:217], v[68:71]
	v_mfma_f32_16x16x32_bf16 v[64:67], v[182:185], v[214:217], v[64:67]
	s_barrier
; #define PG8_STAGE(bufoff, gbase, voff) do { _Pragma("unroll") for (int _i = 0; _i < 2; ++_i) \
;         __builtin_amdgcn_global_load_lds((const unsigned*)((const char*)(gbase) + (voff)[_i]), (PG8_LAS unsigned*)(lds + (bufoff) + ldsw + _i * 8192), 16, 0, 0); } while (0)
; #define PG8_LDA(dst, b, h) do { _Pragma("unroll") for (int m = 0; m < 4; ++m) _Pragma("unroll") for (int k = 0; k < 2; ++k) dst[m][k] = *(const PG8_LAS bf16x8*)(lds + PG8_SA(b, h) + aoff + m * 2048 + k * 1024); } while (0)
; #define PG8_MMA(ai, bj, At, Bt) do { __builtin_amdgcn_s_setprio(1); _Pragma("unroll") for (int m = 0; m < 4; ++m) _Pragma("unroll") for (int n = 0; n < 2; ++n) _Pragma("unroll") for (int k = 0; k < 2; ++k) \
;         acc[ai][bj][m][n] = __builtin_amdgcn_mfma_f32_16x16x32_bf16(Bt[n][k], At[m][k], acc[ai][bj][m][n], 0, 0, 0); __builtin_amdgcn_s_setprio(0); } while (0)
; #define PG8_WAIT_V(n) asm volatile("s_waitcnt vmcnt(" #n ")" ::: "memory")
; #define PG8_WAIT_L(n) asm volatile("s_waitcnt lgkmcnt(" #n ")" ::: "memory")
; #define PG8_BAR __builtin_amdgcn_s_barrier()
; #define PG8_SCHED __builtin_amdgcn_sched_barrier(0)
; template <class Epi, class Sched, bool ALIGN_EPI = false, bool SP2 = false>
; __device__ __forceinline__ void gemm_phase(PG8_LAS unsigned char* lds, const Gemm g, const Sched& S, const Epi& E) {
;     ...
;             PG8_LDA(At, 1, 1); PG8_STAGE(PG8_SB(1, 0), b3, voffB); PG8_STAGE(PG8_SB(1, 1), b3 + hstep, voffB); PG8_STAGE(PG8_SA(1, 0), a3, voffA);
;             PG8_WAIT_V(8); PG8_WAIT_L(0); PG8_BAR; PG8_MMA(1, 0, At, B0); PG8_MMA(1, 1, At, B1); PG8_BAR; PG8_SCHED;
	s_add_i32 s72, s94, s55
	v_lshl_add_u64 v[218:219], v[218:219], 0, s[10:11]
	s_mov_b32 m0, s72
	ds_read_b128 v[186:189], v153 offset:49152
	ds_read_b128 v[190:193], v153 offset:50176
	ds_read_b128 v[194:197], v153 offset:51200
	ds_read_b128 v[198:201], v153 offset:52224
	ds_read_b128 v[202:205], v153 offset:53248
	ds_read_b128 v[206:209], v153 offset:54272
	ds_read_b128 v[210:213], v153 offset:55296
	ds_read_b128 v[214:217], v153 offset:56320
	global_load_lds_dwordx4 v[218:219], off
	s_add_i32 m0, s72, 0x2000
	s_add_u32 s70, s70, 0x80080
	v_lshl_add_u64 v[218:219], v[220:221], 0, s[10:11]
	s_addc_u32 s71, s71, 0
	s_add_i32 s72, s95, s55
	global_load_lds_dwordx4 v[218:219], off
	v_lshl_add_u64 v[218:219], s[70:71], 0, v[130:131]
	s_mov_b32 m0, s72
	s_nop 0
	global_load_lds_dwordx4 v[218:219], off
	v_lshl_add_u64 v[218:219], s[70:71], 0, v[134:135]
	s_add_i32 m0, s72, 0x2000
	s_nop 0
	global_load_lds_dwordx4 v[218:219], off
	v_lshl_add_u64 v[218:219], v[222:223], 0, s[10:11]
	s_mov_b32 m0, s79
	s_nop 0
	global_load_lds_dwordx4 v[218:219], off
	v_lshl_add_u64 v[218:219], v[224:225], 0, s[10:11]
	s_mov_b32 m0, s80
	s_nop 0
	global_load_lds_dwordx4 v[218:219], off
	s_waitcnt vmcnt(8)
	s_waitcnt lgkmcnt(0)
	s_barrier
	s_waitcnt lgkmcnt(0)
	v_mfma_f32_16x16x32_bf16 v[60:63], v[154:157], v[186:189], v[60:63]
	v_mfma_f32_16x16x32_bf16 v[56:59], v[162:165], v[186:189], v[56:59]
	v_mfma_f32_16x16x32_bf16 v[52:55], v[154:157], v[194:197], v[52:55]
	v_mfma_f32_16x16x32_bf16 v[48:51], v[162:165], v[194:197], v[48:51]
	v_mfma_f32_16x16x32_bf16 v[36:39], v[154:157], v[202:205], v[36:39]
	v_mfma_f32_16x16x32_bf16 v[32:35], v[162:165], v[202:205], v[32:35]
	v_mfma_f32_16x16x32_bf16 v[20:23], v[154:157], v[210:213], v[20:23]
	v_mfma_f32_16x16x32_bf16 v[16:19], v[162:165], v[210:213], v[16:19]
	v_mfma_f32_16x16x32_bf16 v[60:63], v[158:161], v[190:193], v[60:63]
	v_mfma_f32_16x16x32_bf16 v[56:59], v[166:169], v[190:193], v[56:59]
	v_mfma_f32_16x16x32_bf16 v[52:55], v[158:161], v[198:201], v[52:55]
	v_mfma_f32_16x16x32_bf16 v[48:51], v[166:169], v[198:201], v[48:51]
	v_mfma_f32_16x16x32_bf16 v[36:39], v[158:161], v[206:209], v[36:39]
	v_mfma_f32_16x16x32_bf16 v[32:35], v[166:169], v[206:209], v[32:35]
	v_mfma_f32_16x16x32_bf16 v[20:23], v[158:161], v[214:217], v[20:23]
	v_mfma_f32_16x16x32_bf16 v[16:19], v[166:169], v[214:217], v[16:19]
	v_mfma_f32_16x16x32_bf16 v[44:47], v[170:173], v[186:189], v[44:47]
	v_mfma_f32_16x16x32_bf16 v[40:43], v[178:181], v[186:189], v[40:43]
	v_mfma_f32_16x16x32_bf16 v[28:31], v[170:173], v[194:197], v[28:31]
	v_mfma_f32_16x16x32_bf16 v[24:27], v[178:181], v[194:197], v[24:27]
	v_mfma_f32_16x16x32_bf16 v[12:15], v[170:173], v[202:205], v[12:15]
	v_mfma_f32_16x16x32_bf16 v[8:11], v[178:181], v[202:205], v[8:11]
	v_mfma_f32_16x16x32_bf16 v[4:7], v[170:173], v[210:213], v[4:7]
	v_mfma_f32_16x16x32_bf16 v[0:3], v[178:181], v[210:213], v[0:3]
	v_mfma_f32_16x16x32_bf16 v[44:47], v[174:177], v[190:193], v[44:47]
	v_mfma_f32_16x16x32_bf16 v[40:43], v[182:185], v[190:193], v[40:43]
	v_mfma_f32_16x16x32_bf16 v[28:31], v[174:177], v[198:201], v[28:31]
	v_mfma_f32_16x16x32_bf16 v[24:27], v[182:185], v[198:201], v[24:27]
	v_mfma_f32_16x16x32_bf16 v[12:15], v[174:177], v[206:209], v[12:15]
	v_mfma_f32_16x16x32_bf16 v[8:11], v[182:185], v[206:209], v[8:11]
	v_mfma_f32_16x16x32_bf16 v[4:7], v[174:177], v[214:217], v[4:7]
	v_mfma_f32_16x16x32_bf16 v[0:3], v[182:185], v[214:217], v[0:3]
	s_barrier
	s_add_i32 s93, s93, 2
	s_add_u32 s68, s68, 0x100
	s_addc_u32 s69, s69, 0
	s_add_u32 s91, s91, 0x100
	s_addc_u32 s92, s92, 0
	s_cmp_gt_u32 s93, 29
	s_cbranch_scc0 .LBB0_119
	s_and_b64 vcc, exec, s[16:17]
	s_cbranch_vccz .LBB0_122
	s_barrier

; #define PG8_STAGE(bufoff, gbase, voff) do { _Pragma("unroll") for (int _i = 0; _i < 2; ++_i) \
;         __builtin_amdgcn_global_load_lds((const unsigned*)((const char*)(gbase) + (voff)[_i]), (PG8_LAS unsigned*)(lds + (bufoff) + ldsw + _i * 8192), 16, 0, 0); } while (0)
; #define PG8_LDA(dst, b, h) do { _Pragma("unroll") for (int m = 0; m < 4; ++m) _Pragma("unroll") for (int k = 0; k < 2; ++k) dst[m][k] = *(const PG8_LAS bf16x8*)(lds + PG8_SA(b, h) + aoff + m * 2048 + k * 1024); } while (0)
; #define PG8_LDB(dst, b, h) do { _Pragma("unroll") for (int n = 0; n < 2; ++n) _Pragma("unroll") for (int k = 0; k < 2; ++k) dst[n][k] = *(const PG8_LAS bf16x8*)(lds + PG8_SB(b, h) + boff + n * 2048 + k * 1024); } while (0)
; #define PG8_MMA(ai, bj, At, Bt) do { __builtin_amdgcn_s_setprio(1); _Pragma("unroll") for (int m = 0; m < 4; ++m) _Pragma("unroll") for (int n = 0; n < 2; ++n) _Pragma("unroll") for (int k = 0; k < 2; ++k) \
;         acc[ai][bj][m][n] = __builtin_amdgcn_mfma_f32_16x16x32_bf16(Bt[n][k], At[m][k], acc[ai][bj][m][n], 0, 0, 0); __builtin_amdgcn_s_setprio(0); } while (0)
; #define PG8_WAIT_V(n) asm volatile("s_waitcnt vmcnt(" #n ")" ::: "memory")
; #define PG8_WAIT_L(n) asm volatile("s_waitcnt lgkmcnt(" #n ")" ::: "memory")
; template <class Epi, class Sched, bool ALIGN_EPI = false, bool SP2 = false>
; __device__ __forceinline__ void gemm_phase(PG8_LAS unsigned char* lds, const Gemm g, const Sched& S, const Epi& E) {
;     ...
;             const bool last = (t == nt - 2);
;             const char* a1 = cA + (size_t)(t + 1) * kstep;
;             const char* a2 = last ? nA : cA + (size_t)(t + 2) * kstep; const char* b2 = last ? nB : cB + (size_t)(t + 2) * kstep;
;             const char* a3 = a2 + kstep; const char* b3 = b2 + kstep;
;             if (last && has_next) S.a_ready(nxt);
;             if constexpr (SP2) {
;             PG8_LDB(B0, 0, 0); PG8_LDB(B1, 0, 1); PG8_SCHED; PG8_LDA(At, 0, 0); PG8_STAGE(PG8_SA(1, 1), a1 + hstep, voffA);
;             PG8_WAIT_V(8); PG8_WAIT_L(0); PG8_BAR; PG8_MMA(0, 0, At, B0); PG8_MMA(0, 1, At, B1); PG8_BAR; PG8_SCHED;
;             PG8_LDA(At, 0, 1); PG8_STAGE(PG8_SB(0, 0), b2, voffB); PG8_STAGE(PG8_SB(0, 1), b2 + hstep, voffB); PG8_STAGE(PG8_SA(0, 0), a2, voffA);
;             PG8_WAIT_V(8); PG8_WAIT_L(0); PG8_BAR; PG8_MMA(1, 0, At, B0); PG8_MMA(1, 1, At, B1); PG8_BAR; PG8_SCHED;
.LBB0_559:
	ds_read_b128 v[148:151], v145
	ds_read_b128 v[152:155], v145 offset:1024
	ds_read_b128 v[156:159], v145 offset:2048
	ds_read_b128 v[160:163], v145 offset:3072
	ds_read_b128 v[164:167], v146
	ds_read_b128 v[168:171], v146 offset:1024
	ds_read_b128 v[172:175], v146 offset:2048
	ds_read_b128 v[176:179], v146 offset:3072
	s_add_u32 s38, s36, 0x100
	s_addc_u32 s39, s37, 0
	s_cmp_eq_u32 s85, 28
	s_cselect_b32 s67, s25, s39
	s_cselect_b32 s66, s81, s38
	s_cselect_b32 s45, s23, s84
	s_cselect_b32 s44, s82, s83
	v_lshl_add_u64 v[140:141], s[36:37], 0, v[132:133]
	s_add_i32 m0, s68, 0xc000
	ds_read_b128 v[180:183], v147
	ds_read_b128 v[184:187], v147 offset:1024
	ds_read_b128 v[188:191], v147 offset:2048
	ds_read_b128 v[192:195], v147 offset:3072
	ds_read_b128 v[196:199], v147 offset:4096
	ds_read_b128 v[200:203], v147 offset:5120
	ds_read_b128 v[204:207], v147 offset:6144
	ds_read_b128 v[208:211], v147 offset:7168
	global_load_lds_dwordx4 v[140:141], off
	v_lshl_add_u64 v[140:141], s[36:37], 0, v[134:135]
	s_add_i32 m0, s68, 0xe000
	s_nop 0
	global_load_lds_dwordx4 v[140:141], off
	s_waitcnt vmcnt(8)
	s_waitcnt lgkmcnt(0)
	s_barrier
	s_waitcnt lgkmcnt(0)
	v_mfma_f32_16x16x32_bf16 v[124:127], v[148:151], v[180:183], v[124:127]
	v_mfma_f32_16x16x32_bf16 v[120:123], v[156:159], v[180:183], v[120:123]
	v_mfma_f32_16x16x32_bf16 v[112:115], v[148:151], v[188:191], v[112:115]
	v_mfma_f32_16x16x32_bf16 v[108:111], v[156:159], v[188:191], v[108:111]
	v_mfma_f32_16x16x32_bf16 v[96:99], v[148:151], v[196:199], v[96:99]
	v_mfma_f32_16x16x32_bf16 v[92:95], v[156:159], v[196:199], v[92:95]
	v_mfma_f32_16x16x32_bf16 v[80:83], v[148:151], v[204:207], v[80:83]
	v_mfma_f32_16x16x32_bf16 v[76:79], v[156:159], v[204:207], v[76:79]
	v_mfma_f32_16x16x32_bf16 v[124:127], v[152:155], v[184:187], v[124:127]
	v_mfma_f32_16x16x32_bf16 v[120:123], v[160:163], v[184:187], v[120:123]
	v_mfma_f32_16x16x32_bf16 v[112:115], v[152:155], v[192:195], v[112:115]
	v_mfma_f32_16x16x32_bf16 v[108:111], v[160:163], v[192:195], v[108:111]
	v_mfma_f32_16x16x32_bf16 v[96:99], v[152:155], v[200:203], v[96:99]
	v_mfma_f32_16x16x32_bf16 v[92:95], v[160:163], v[200:203], v[92:95]
	v_mfma_f32_16x16x32_bf16 v[80:83], v[152:155], v[208:211], v[80:83]
	v_mfma_f32_16x16x32_bf16 v[76:79], v[160:163], v[208:211], v[76:79]
	v_mfma_f32_16x16x32_bf16 v[116:119], v[164:167], v[180:183], v[116:119]
	v_mfma_f32_16x16x32_bf16 v[104:107], v[172:175], v[180:183], v[104:107]
	v_mfma_f32_16x16x32_bf16 v[100:103], v[164:167], v[188:191], v[100:103]
	v_mfma_f32_16x16x32_bf16 v[88:91], v[172:175], v[188:191], v[88:91]
	v_mfma_f32_16x16x32_bf16 v[84:87], v[164:167], v[196:199], v[84:87]
	v_mfma_f32_16x16x32_bf16 v[72:75], v[172:175], v[196:199], v[72:75]
	v_mfma_f32_16x16x32_bf16 v[68:71], v[164:167], v[204:207], v[68:71]
	v_mfma_f32_16x16x32_bf16 v[64:67], v[172:175], v[204:207], v[64:67]
	v_mfma_f32_16x16x32_bf16 v[116:119], v[168:171], v[184:187], v[116:119]
	v_mfma_f32_16x16x32_bf16 v[104:107], v[176:179], v[184:187], v[104:107]
	v_mfma_f32_16x16x32_bf16 v[100:103], v[168:171], v[192:195], v[100:103]
	v_mfma_f32_16x16x32_bf16 v[88:91], v[176:179], v[192:195], v[88:91]
	v_mfma_f32_16x16x32_bf16 v[84:87], v[168:171], v[200:203], v[84:87]
	v_mfma_f32_16x16x32_bf16 v[72:75], v[176:179], v[200:203], v[72:75]
	v_mfma_f32_16x16x32_bf16 v[68:71], v[168:171], v[208:211], v[68:71]
	v_mfma_f32_16x16x32_bf16 v[64:67], v[176:179], v[208:211], v[64:67]
	s_barrier
	s_add_i32 s36, s79, s3
	v_lshl_add_u64 v[140:141], s[44:45], 0, v[130:131]
	s_mov_b32 m0, s36
	ds_read_b128 v[180:183], v147 offset:16384
	ds_read_b128 v[184:187], v147 offset:17408
	ds_read_b128 v[188:191], v147 offset:18432
	ds_read_b128 v[192:195], v147 offset:19456
	ds_read_b128 v[196:199], v147 offset:20480
	ds_read_b128 v[200:203], v147 offset:21504
	ds_read_b128 v[204:207], v147 offset:22528
	ds_read_b128 v[208:211], v147 offset:23552
	global_load_lds_dwordx4 v[140:141], off
	s_add_i32 m0, s36, 0x2000
	s_add_u32 s36, s44, 0x80000
	v_lshl_add_u64 v[212:213], s[44:45], 0, v[128:129]
	s_addc_u32 s37, s45, 0
	s_add_i32 s86, s80, s3
	global_load_lds_dwordx4 v[212:213], off
	v_lshl_add_u64 v[214:215], s[36:37], 0, v[130:131]
	s_mov_b32 m0, s86
	v_lshl_add_u64 v[216:217], s[66:67], 0, v[128:129]
	global_load_lds_dwordx4 v[214:215], off
	v_lshl_add_u64 v[214:215], s[36:37], 0, v[128:129]
	s_add_i32 m0, s86, 0x2000
	s_nop 0
	global_load_lds_dwordx4 v[214:215], off
	v_lshl_add_u64 v[214:215], s[66:67], 0, v[130:131]
	s_mov_b32 m0, s68
	s_nop 0
	global_load_lds_dwordx4 v[214:215], off
	s_mov_b32 m0, s69
	s_nop 0
	global_load_lds_dwordx4 v[216:217], off
	s_waitcnt vmcnt(8)
	s_waitcnt lgkmcnt(0)
	s_barrier
; #define PG8_STAGE(bufoff, gbase, voff) do { _Pragma("unroll") for (int _i = 0; _i < 2; ++_i) \
;         __builtin_amdgcn_global_load_lds((const unsigned*)((const char*)(gbase) + (voff)[_i]), (PG8_LAS unsigned*)(lds + (bufoff) + ldsw + _i * 8192), 16, 0, 0); } while (0)
; #define PG8_LDA(dst, b, h) do { _Pragma("unroll") for (int m = 0; m < 4; ++m) _Pragma("unroll") for (int k = 0; k < 2; ++k) dst[m][k] = *(const PG8_LAS bf16x8*)(lds + PG8_SA(b, h) + aoff + m * 2048 + k * 1024); } while (0)
; #define PG8_LDB(dst, b, h) do { _Pragma("unroll") for (int n = 0; n < 2; ++n) _Pragma("unroll") for (int k = 0; k < 2; ++k) dst[n][k] = *(const PG8_LAS bf16x8*)(lds + PG8_SB(b, h) + boff + n * 2048 + k * 1024); } while (0)
; #define PG8_MMA(ai, bj, At, Bt) do { __builtin_amdgcn_s_setprio(1); _Pragma("unroll") for (int m = 0; m < 4; ++m) _Pragma("unroll") for (int n = 0; n < 2; ++n) _Pragma("unroll") for (int k = 0; k < 2; ++k) \
;         acc[ai][bj][m][n] = __builtin_amdgcn_mfma_f32_16x16x32_bf16(Bt[n][k], At[m][k], acc[ai][bj][m][n], 0, 0, 0); __builtin_amdgcn_s_setprio(0); } while (0)
; #define PG8_WAIT_V(n) asm volatile("s_waitcnt vmcnt(" #n ")" ::: "memory")
; #define PG8_WAIT_L(n) asm volatile("s_waitcnt lgkmcnt(" #n ")" ::: "memory")
; #define PG8_BAR __builtin_amdgcn_s_barrier()
; #define PG8_SCHED __builtin_amdgcn_sched_barrier(0)
; template <class Epi, class Sched, bool ALIGN_EPI = false, bool SP2 = false>
; __device__ __forceinline__ void gemm_phase(PG8_LAS unsigned char* lds, const Gemm g, const Sched& S, const Epi& E) {
;     ...
;             PG8_WAIT_V(8); PG8_WAIT_L(0); PG8_BAR; PG8_MMA(1, 0, At, B0); PG8_MMA(1, 1, At, B1); PG8_BAR; PG8_SCHED;
;             PG8_LDB(B0, 1, 0); PG8_LDB(B1, 1, 1); PG8_SCHED; PG8_LDA(At, 1, 0); PG8_STAGE(PG8_SA(0, 1), a2 + hstep, voffA);
;             PG8_WAIT_V(8); PG8_WAIT_L(0); PG8_BAR; PG8_MMA(0, 0, At, B0); PG8_MMA(0, 1, At, B1); PG8_BAR; PG8_SCHED;
	s_waitcnt lgkmcnt(0)
	v_mfma_f32_16x16x32_bf16 v[60:63], v[148:151], v[180:183], v[60:63]
	v_mfma_f32_16x16x32_bf16 v[56:59], v[156:159], v[180:183], v[56:59]
	v_mfma_f32_16x16x32_bf16 v[48:51], v[148:151], v[188:191], v[48:51]
	v_mfma_f32_16x16x32_bf16 v[44:47], v[156:159], v[188:191], v[44:47]
	v_mfma_f32_16x16x32_bf16 v[32:35], v[148:151], v[196:199], v[32:35]
	v_mfma_f32_16x16x32_bf16 v[28:31], v[156:159], v[196:199], v[28:31]
	v_mfma_f32_16x16x32_bf16 v[16:19], v[148:151], v[204:207], v[16:19]
	v_mfma_f32_16x16x32_bf16 v[12:15], v[156:159], v[204:207], v[12:15]
	v_mfma_f32_16x16x32_bf16 v[60:63], v[152:155], v[184:187], v[60:63]
	v_mfma_f32_16x16x32_bf16 v[56:59], v[160:163], v[184:187], v[56:59]
	v_mfma_f32_16x16x32_bf16 v[48:51], v[152:155], v[192:195], v[48:51]
	v_mfma_f32_16x16x32_bf16 v[44:47], v[160:163], v[192:195], v[44:47]
	v_mfma_f32_16x16x32_bf16 v[32:35], v[152:155], v[200:203], v[32:35]
	v_mfma_f32_16x16x32_bf16 v[28:31], v[160:163], v[200:203], v[28:31]
	v_mfma_f32_16x16x32_bf16 v[16:19], v[152:155], v[208:211], v[16:19]
	v_mfma_f32_16x16x32_bf16 v[12:15], v[160:163], v[208:211], v[12:15]
	v_mfma_f32_16x16x32_bf16 v[52:55], v[164:167], v[180:183], v[52:55]
	v_mfma_f32_16x16x32_bf16 v[40:43], v[172:175], v[180:183], v[40:43]
	v_mfma_f32_16x16x32_bf16 v[36:39], v[164:167], v[188:191], v[36:39]
	v_mfma_f32_16x16x32_bf16 v[24:27], v[172:175], v[188:191], v[24:27]
	v_mfma_f32_16x16x32_bf16 v[20:23], v[164:167], v[196:199], v[20:23]
	v_mfma_f32_16x16x32_bf16 v[8:11], v[172:175], v[196:199], v[8:11]
	v_mfma_f32_16x16x32_bf16 v[4:7], v[164:167], v[204:207], v[4:7]
	v_mfma_f32_16x16x32_bf16 v[0:3], v[172:175], v[204:207], v[0:3]
	v_mfma_f32_16x16x32_bf16 v[52:55], v[168:171], v[184:187], v[52:55]
	v_mfma_f32_16x16x32_bf16 v[40:43], v[176:179], v[184:187], v[40:43]
	v_mfma_f32_16x16x32_bf16 v[36:39], v[168:171], v[192:195], v[36:39]
	v_mfma_f32_16x16x32_bf16 v[24:27], v[176:179], v[192:195], v[24:27]
	v_mfma_f32_16x16x32_bf16 v[20:23], v[168:171], v[200:203], v[20:23]
	v_mfma_f32_16x16x32_bf16 v[8:11], v[176:179], v[200:203], v[8:11]
	v_mfma_f32_16x16x32_bf16 v[4:7], v[168:171], v[208:211], v[4:7]
	v_mfma_f32_16x16x32_bf16 v[0:3], v[176:179], v[208:211], v[0:3]
	s_barrier
	s_add_i32 s86, 0, 0x18000
	s_add_i32 s87, 0, 0x1c000
	v_add_u32_e32 v160, s86, v143
	v_add_u32_e32 v176, s87, v143
	ds_read_b128 v[148:151], v160
	ds_read_b128 v[152:155], v160 offset:1024
	ds_read_b128 v[156:159], v160 offset:2048
	ds_read_b128 v[160:163], v160 offset:3072
	ds_read_b128 v[164:167], v176
	ds_read_b128 v[168:171], v176 offset:1024
	ds_read_b128 v[172:175], v176 offset:2048
	ds_read_b128 v[176:179], v176 offset:3072
	s_add_u32 s36, s66, 0x80000
	s_addc_u32 s37, s67, 0
	s_mov_b32 m0, s70
	v_lshl_add_u64 v[218:219], s[36:37], 0, v[130:131]
	ds_read_b128 v[180:183], v147 offset:32768
	ds_read_b128 v[184:187], v147 offset:33792
	ds_read_b128 v[188:191], v147 offset:34816
	ds_read_b128 v[192:195], v147 offset:35840
	ds_read_b128 v[196:199], v147 offset:36864
	ds_read_b128 v[200:203], v147 offset:37888
	ds_read_b128 v[204:207], v147 offset:38912
	ds_read_b128 v[208:211], v147 offset:39936
	global_load_lds_dwordx4 v[218:219], off
	v_lshl_add_u64 v[218:219], s[36:37], 0, v[128:129]
	s_mov_b32 m0, s71
	s_nop 0
	global_load_lds_dwordx4 v[218:219], off
	s_waitcnt vmcnt(8)
	s_waitcnt lgkmcnt(0)
	s_barrier
	s_waitcnt lgkmcnt(0)
	v_mfma_f32_16x16x32_bf16 v[124:127], v[148:151], v[180:183], v[124:127]
	v_mfma_f32_16x16x32_bf16 v[120:123], v[156:159], v[180:183], v[120:123]
	v_mfma_f32_16x16x32_bf16 v[112:115], v[148:151], v[188:191], v[112:115]
	v_mfma_f32_16x16x32_bf16 v[108:111], v[156:159], v[188:191], v[108:111]
	v_mfma_f32_16x16x32_bf16 v[96:99], v[148:151], v[196:199], v[96:99]
	v_mfma_f32_16x16x32_bf16 v[92:95], v[156:159], v[196:199], v[92:95]
	v_mfma_f32_16x16x32_bf16 v[80:83], v[148:151], v[204:207], v[80:83]
	v_mfma_f32_16x16x32_bf16 v[76:79], v[156:159], v[204:207], v[76:79]
	v_mfma_f32_16x16x32_bf16 v[124:127], v[152:155], v[184:187], v[124:127]
	v_mfma_f32_16x16x32_bf16 v[120:123], v[160:163], v[184:187], v[120:123]
	v_mfma_f32_16x16x32_bf16 v[112:115], v[152:155], v[192:195], v[112:115]
	v_mfma_f32_16x16x32_bf16 v[108:111], v[160:163], v[192:195], v[108:111]
	v_mfma_f32_16x16x32_bf16 v[96:99], v[152:155], v[200:203], v[96:99]
	v_mfma_f32_16x16x32_bf16 v[92:95], v[160:163], v[200:203], v[92:95]
	v_mfma_f32_16x16x32_bf16 v[80:83], v[152:155], v[208:211], v[80:83]
	v_mfma_f32_16x16x32_bf16 v[76:79], v[160:163], v[208:211], v[76:79]
	v_mfma_f32_16x16x32_bf16 v[116:119], v[164:167], v[180:183], v[116:119]
	v_mfma_f32_16x16x32_bf16 v[104:107], v[172:175], v[180:183], v[104:107]
	v_mfma_f32_16x16x32_bf16 v[100:103], v[164:167], v[188:191], v[100:103]
	v_mfma_f32_16x16x32_bf16 v[88:91], v[172:175], v[188:191], v[88:91]
	v_mfma_f32_16x16x32_bf16 v[84:87], v[164:167], v[196:199], v[84:87]
	v_mfma_f32_16x16x32_bf16 v[72:75], v[172:175], v[196:199], v[72:75]
	v_mfma_f32_16x16x32_bf16 v[68:71], v[164:167], v[204:207], v[68:71]
	v_mfma_f32_16x16x32_bf16 v[64:67], v[172:175], v[204:207], v[64:67]
	v_mfma_f32_16x16x32_bf16 v[116:119], v[168:171], v[184:187], v[116:119]
	v_mfma_f32_16x16x32_bf16 v[104:107], v[176:179], v[184:187], v[104:107]
	v_mfma_f32_16x16x32_bf16 v[100:103], v[168:171], v[192:195], v[100:103]
	v_mfma_f32_16x16x32_bf16 v[88:91], v[176:179], v[192:195], v[88:91]
	v_mfma_f32_16x16x32_bf16 v[84:87], v[168:171], v[200:203], v[84:87]
	v_mfma_f32_16x16x32_bf16 v[72:75], v[176:179], v[200:203], v[72:75]
	v_mfma_f32_16x16x32_bf16 v[68:71], v[168:171], v[208:211], v[68:71]
	v_mfma_f32_16x16x32_bf16 v[64:67], v[176:179], v[208:211], v[64:67]
	s_barrier
; #define PG8_STAGE(bufoff, gbase, voff) do { _Pragma("unroll") for (int _i = 0; _i < 2; ++_i) \
;         __builtin_amdgcn_global_load_lds((const unsigned*)((const char*)(gbase) + (voff)[_i]), (PG8_LAS unsigned*)(lds + (bufoff) + ldsw + _i * 8192), 16, 0, 0); } while (0)
; #define PG8_LDA(dst, b, h) do { _Pragma("unroll") for (int m = 0; m < 4; ++m) _Pragma("unroll") for (int k = 0; k < 2; ++k) dst[m][k] = *(const PG8_LAS bf16x8*)(lds + PG8_SA(b, h) + aoff + m * 2048 + k * 1024); } while (0)
; #define PG8_MMA(ai, bj, At, Bt) do { __builtin_amdgcn_s_setprio(1); _Pragma("unroll") for (int m = 0; m < 4; ++m) _Pragma("unroll") for (int n = 0; n < 2; ++n) _Pragma("unroll") for (int k = 0; k < 2; ++k) \
;         acc[ai][bj][m][n] = __builtin_amdgcn_mfma_f32_16x16x32_bf16(Bt[n][k], At[m][k], acc[ai][bj][m][n], 0, 0, 0); __builtin_amdgcn_s_setprio(0); } while (0)
; #define PG8_WAIT_V(n) asm volatile("s_waitcnt vmcnt(" #n ")" ::: "memory")
; #define PG8_WAIT_L(n) asm volatile("s_waitcnt lgkmcnt(" #n ")" ::: "memory")
; #define PG8_BAR __builtin_amdgcn_s_barrier()
; #define PG8_SCHED __builtin_amdgcn_sched_barrier(0)
; template <class Epi, class Sched, bool ALIGN_EPI = false, bool SP2 = false>
; __device__ __forceinline__ void gemm_phase(PG8_LAS unsigned char* lds, const Gemm g, const Sched& S, const Epi& E) {
;     ...
;             PG8_LDA(At, 1, 1); PG8_STAGE(PG8_SB(1, 0), b3, voffB); PG8_STAGE(PG8_SB(1, 1), b3 + hstep, voffB); PG8_STAGE(PG8_SA(1, 0), a3, voffA);
;             PG8_WAIT_V(8); PG8_WAIT_L(0); PG8_BAR; PG8_MMA(1, 0, At, B0); PG8_MMA(1, 1, At, B1); PG8_BAR; PG8_SCHED;
	s_add_i32 s36, s86, s3
	v_lshl_add_u64 v[140:141], v[140:141], 0, s[8:9]
	s_mov_b32 m0, s36
	ds_read_b128 v[180:183], v147 offset:49152
	ds_read_b128 v[184:187], v147 offset:50176
	ds_read_b128 v[188:191], v147 offset:51200
	ds_read_b128 v[192:195], v147 offset:52224
	ds_read_b128 v[196:199], v147 offset:53248
	ds_read_b128 v[200:203], v147 offset:54272
	ds_read_b128 v[204:207], v147 offset:55296
	ds_read_b128 v[208:211], v147 offset:56320
	global_load_lds_dwordx4 v[140:141], off
	s_add_i32 m0, s36, 0x2000
	s_add_u32 s36, s44, 0x80080
	v_lshl_add_u64 v[140:141], v[212:213], 0, s[8:9]
	s_addc_u32 s37, s45, 0
	s_add_i32 s44, s87, s3
	global_load_lds_dwordx4 v[140:141], off
	v_lshl_add_u64 v[140:141], s[36:37], 0, v[130:131]
	s_mov_b32 m0, s44
	s_nop 0
	global_load_lds_dwordx4 v[140:141], off
	v_lshl_add_u64 v[140:141], s[36:37], 0, v[128:129]
	s_add_i32 m0, s44, 0x2000
	s_nop 0
	global_load_lds_dwordx4 v[140:141], off
	v_lshl_add_u64 v[140:141], v[214:215], 0, s[8:9]
	s_mov_b32 m0, s75
	s_nop 0
	global_load_lds_dwordx4 v[140:141], off
	v_lshl_add_u64 v[140:141], v[216:217], 0, s[8:9]
	s_mov_b32 m0, s76
	s_nop 0
	global_load_lds_dwordx4 v[140:141], off
	s_waitcnt vmcnt(8)
	s_waitcnt lgkmcnt(0)
	s_barrier
	s_waitcnt lgkmcnt(0)
	v_mfma_f32_16x16x32_bf16 v[60:63], v[148:151], v[180:183], v[60:63]
	v_mfma_f32_16x16x32_bf16 v[56:59], v[156:159], v[180:183], v[56:59]
	v_mfma_f32_16x16x32_bf16 v[48:51], v[148:151], v[188:191], v[48:51]
	v_mfma_f32_16x16x32_bf16 v[44:47], v[156:159], v[188:191], v[44:47]
	v_mfma_f32_16x16x32_bf16 v[32:35], v[148:151], v[196:199], v[32:35]
	v_mfma_f32_16x16x32_bf16 v[28:31], v[156:159], v[196:199], v[28:31]
	v_mfma_f32_16x16x32_bf16 v[16:19], v[148:151], v[204:207], v[16:19]
	v_mfma_f32_16x16x32_bf16 v[12:15], v[156:159], v[204:207], v[12:15]
	v_mfma_f32_16x16x32_bf16 v[60:63], v[152:155], v[184:187], v[60:63]
	v_mfma_f32_16x16x32_bf16 v[56:59], v[160:163], v[184:187], v[56:59]
	v_mfma_f32_16x16x32_bf16 v[48:51], v[152:155], v[192:195], v[48:51]
	v_mfma_f32_16x16x32_bf16 v[44:47], v[160:163], v[192:195], v[44:47]
	v_mfma_f32_16x16x32_bf16 v[32:35], v[152:155], v[200:203], v[32:35]
	v_mfma_f32_16x16x32_bf16 v[28:31], v[160:163], v[200:203], v[28:31]
	v_mfma_f32_16x16x32_bf16 v[16:19], v[152:155], v[208:211], v[16:19]
	v_mfma_f32_16x16x32_bf16 v[12:15], v[160:163], v[208:211], v[12:15]
	v_mfma_f32_16x16x32_bf16 v[52:55], v[164:167], v[180:183], v[52:55]
	v_mfma_f32_16x16x32_bf16 v[40:43], v[172:175], v[180:183], v[40:43]
	v_mfma_f32_16x16x32_bf16 v[36:39], v[164:167], v[188:191], v[36:39]
	v_mfma_f32_16x16x32_bf16 v[24:27], v[172:175], v[188:191], v[24:27]
	v_mfma_f32_16x16x32_bf16 v[20:23], v[164:167], v[196:199], v[20:23]
	v_mfma_f32_16x16x32_bf16 v[8:11], v[172:175], v[196:199], v[8:11]
	v_mfma_f32_16x16x32_bf16 v[4:7], v[164:167], v[204:207], v[4:7]
	v_mfma_f32_16x16x32_bf16 v[0:3], v[172:175], v[204:207], v[0:3]
	v_mfma_f32_16x16x32_bf16 v[52:55], v[168:171], v[184:187], v[52:55]
	v_mfma_f32_16x16x32_bf16 v[40:43], v[176:179], v[184:187], v[40:43]
	v_mfma_f32_16x16x32_bf16 v[36:39], v[168:171], v[192:195], v[36:39]
	v_mfma_f32_16x16x32_bf16 v[24:27], v[176:179], v[192:195], v[24:27]
	v_mfma_f32_16x16x32_bf16 v[20:23], v[168:171], v[200:203], v[20:23]
	v_mfma_f32_16x16x32_bf16 v[8:11], v[176:179], v[200:203], v[8:11]
	v_mfma_f32_16x16x32_bf16 v[4:7], v[168:171], v[208:211], v[4:7]
	v_mfma_f32_16x16x32_bf16 v[0:3], v[176:179], v[208:211], v[0:3]
	s_barrier
	s_add_i32 s85, s85, 2
	s_add_u32 s83, s83, 0x100
	s_addc_u32 s84, s84, 0
	s_cmp_gt_u32 s85, 29
	s_mov_b64 s[36:37], s[38:39]
	s_cbranch_scc0 .LBB0_559
	s_and_b64 vcc, exec, s[10:11]
	s_cbranch_vccz .LBB0_562
	s_barrier

; #define PG8_STAGE(bufoff, gbase, voff) do { _Pragma("unroll") for (int _i = 0; _i < 2; ++_i) \
;         __builtin_amdgcn_global_load_lds((const unsigned*)((const char*)(gbase) + (voff)[_i]), (PG8_LAS unsigned*)(lds + (bufoff) + ldsw + _i * 8192), 16, 0, 0); } while (0)
; #define PG8_LDA(dst, b, h) do { _Pragma("unroll") for (int m = 0; m < 4; ++m) _Pragma("unroll") for (int k = 0; k < 2; ++k) dst[m][k] = *(const PG8_LAS bf16x8*)(lds + PG8_SA(b, h) + aoff + m * 2048 + k * 1024); } while (0)
; #define PG8_LDB(dst, b, h) do { _Pragma("unroll") for (int n = 0; n < 2; ++n) _Pragma("unroll") for (int k = 0; k < 2; ++k) dst[n][k] = *(const PG8_LAS bf16x8*)(lds + PG8_SB(b, h) + boff + n * 2048 + k * 1024); } while (0)
; #define PG8_MMA(ai, bj, At, Bt) do { __builtin_amdgcn_s_setprio(1); _Pragma("unroll") for (int m = 0; m < 4; ++m) _Pragma("unroll") for (int n = 0; n < 2; ++n) _Pragma("unroll") for (int k = 0; k < 2; ++k) \
;         acc[ai][bj][m][n] = __builtin_amdgcn_mfma_f32_16x16x32_bf16(Bt[n][k], At[m][k], acc[ai][bj][m][n], 0, 0, 0); __builtin_amdgcn_s_setprio(0); } while (0)
; #define PG8_WAIT_V(n) asm volatile("s_waitcnt vmcnt(" #n ")" ::: "memory")
; #define PG8_WAIT_L(n) asm volatile("s_waitcnt lgkmcnt(" #n ")" ::: "memory")
; template <class Epi, class Sched, bool ALIGN_EPI = false, bool SP2 = false>
; __device__ __forceinline__ void gemm_phase(PG8_LAS unsigned char* lds, const Gemm g, const Sched& S, const Epi& E) {
;     ...
;             const bool last = (t == nt - 2);
;             const char* a1 = cA + (size_t)(t + 1) * kstep;
;             const char* a2 = last ? nA : cA + (size_t)(t + 2) * kstep; const char* b2 = last ? nB : cB + (size_t)(t + 2) * kstep;
;             const char* a3 = a2 + kstep; const char* b3 = b2 + kstep;
;             if (last && has_next) S.a_ready(nxt);
;             if constexpr (SP2) {
;             PG8_LDB(B0, 0, 0); PG8_LDB(B1, 0, 1); PG8_SCHED; PG8_LDA(At, 0, 0); PG8_STAGE(PG8_SA(1, 1), a1 + hstep, voffA);
;             PG8_WAIT_V(8); PG8_WAIT_L(0); PG8_BAR; PG8_MMA(0, 0, At, B0); PG8_MMA(0, 1, At, B1); PG8_BAR; PG8_SCHED;
;             PG8_LDA(At, 0, 1); PG8_STAGE(PG8_SB(0, 0), b2, voffB); PG8_STAGE(PG8_SB(0, 1), b2 + hstep, voffB); PG8_STAGE(PG8_SA(0, 0), a2, voffA);
;             PG8_WAIT_V(8); PG8_WAIT_L(0); PG8_BAR; PG8_MMA(1, 0, At, B0); PG8_MMA(1, 1, At, B1); PG8_BAR; PG8_SCHED;
.LBB0_704:
	s_add_u32 s10, s8, 0xfff80080
	s_addc_u32 s11, s9, -1
	s_add_i32 s35, 0, 0x10000
	s_cmp_eq_u32 s34, 28
	s_cselect_b32 s13, s31, s11
	s_cselect_b32 s12, s74, s10
	v_add_u32_e32 v142, s35, v146
	s_cselect_b32 s11, s39, vcc_hi
	s_cselect_b32 s10, s89, vcc_lo
	s_add_i32 s54, 0, 0x14000
	ds_read_b128 v[150:153], v142
	ds_read_b128 v[154:157], v142 offset:1024
	ds_read_b128 v[158:161], v142 offset:2048
	ds_read_b128 v[162:165], v142 offset:3072
	v_add_u32_e32 v142, s54, v146
	ds_read_b128 v[166:169], v142
	ds_read_b128 v[170:173], v142 offset:1024
	ds_read_b128 v[174:177], v142 offset:2048
	ds_read_b128 v[178:181], v142 offset:3072
	v_lshl_add_u64 v[142:143], s[8:9], 0, v[136:137]
	s_add_i32 m0, s25, 0xc000
	ds_read_b128 v[182:185], v148
	ds_read_b128 v[186:189], v148 offset:1024
	ds_read_b128 v[190:193], v148 offset:2048
	ds_read_b128 v[194:197], v148 offset:3072
	ds_read_b128 v[198:201], v148 offset:4096
	ds_read_b128 v[202:205], v148 offset:5120
	ds_read_b128 v[206:209], v148 offset:6144
	ds_read_b128 v[210:213], v148 offset:7168
	global_load_lds_dwordx4 v[142:143], off
	v_lshl_add_u64 v[142:143], s[8:9], 0, v[138:139]
	s_add_i32 m0, s25, 0xe000
	s_nop 0
	global_load_lds_dwordx4 v[142:143], off
	s_waitcnt vmcnt(8)
	s_waitcnt lgkmcnt(0)
	s_barrier
	s_waitcnt lgkmcnt(0)
	v_mfma_f32_16x16x32_bf16 v[124:127], v[150:153], v[182:185], v[124:127]
	v_mfma_f32_16x16x32_bf16 v[120:123], v[158:161], v[182:185], v[120:123]
	v_mfma_f32_16x16x32_bf16 v[108:111], v[150:153], v[190:193], v[108:111]
	v_mfma_f32_16x16x32_bf16 v[104:107], v[158:161], v[190:193], v[104:107]
	v_mfma_f32_16x16x32_bf16 v[92:95], v[150:153], v[198:201], v[92:95]
	v_mfma_f32_16x16x32_bf16 v[88:91], v[158:161], v[198:201], v[88:91]
	v_mfma_f32_16x16x32_bf16 v[76:79], v[150:153], v[206:209], v[76:79]
	v_mfma_f32_16x16x32_bf16 v[72:75], v[158:161], v[206:209], v[72:75]
	v_mfma_f32_16x16x32_bf16 v[124:127], v[154:157], v[186:189], v[124:127]
	v_mfma_f32_16x16x32_bf16 v[120:123], v[162:165], v[186:189], v[120:123]
	v_mfma_f32_16x16x32_bf16 v[108:111], v[154:157], v[194:197], v[108:111]
	v_mfma_f32_16x16x32_bf16 v[104:107], v[162:165], v[194:197], v[104:107]
	v_mfma_f32_16x16x32_bf16 v[92:95], v[154:157], v[202:205], v[92:95]
	v_mfma_f32_16x16x32_bf16 v[88:91], v[162:165], v[202:205], v[88:91]
	v_mfma_f32_16x16x32_bf16 v[76:79], v[154:157], v[210:213], v[76:79]
	v_mfma_f32_16x16x32_bf16 v[72:75], v[162:165], v[210:213], v[72:75]
	v_mfma_f32_16x16x32_bf16 v[116:119], v[166:169], v[182:185], v[116:119]
	v_mfma_f32_16x16x32_bf16 v[112:115], v[174:177], v[182:185], v[112:115]
	v_mfma_f32_16x16x32_bf16 v[100:103], v[166:169], v[190:193], v[100:103]
	v_mfma_f32_16x16x32_bf16 v[96:99], v[174:177], v[190:193], v[96:99]
	v_mfma_f32_16x16x32_bf16 v[84:87], v[166:169], v[198:201], v[84:87]
	v_mfma_f32_16x16x32_bf16 v[80:83], v[174:177], v[198:201], v[80:83]
	v_mfma_f32_16x16x32_bf16 v[68:71], v[166:169], v[206:209], v[68:71]
	v_mfma_f32_16x16x32_bf16 v[64:67], v[174:177], v[206:209], v[64:67]
	v_mfma_f32_16x16x32_bf16 v[116:119], v[170:173], v[186:189], v[116:119]
	v_mfma_f32_16x16x32_bf16 v[112:115], v[178:181], v[186:189], v[112:115]
	v_mfma_f32_16x16x32_bf16 v[100:103], v[170:173], v[194:197], v[100:103]
	v_mfma_f32_16x16x32_bf16 v[96:99], v[178:181], v[194:197], v[96:99]
	v_mfma_f32_16x16x32_bf16 v[84:87], v[170:173], v[202:205], v[84:87]
	v_mfma_f32_16x16x32_bf16 v[80:83], v[178:181], v[202:205], v[80:83]
	v_mfma_f32_16x16x32_bf16 v[68:71], v[170:173], v[210:213], v[68:71]
	v_mfma_f32_16x16x32_bf16 v[64:67], v[178:181], v[210:213], v[64:67]
	s_barrier
	s_add_i32 s35, s35, s24
	v_lshl_add_u64 v[142:143], s[10:11], 0, v[128:129]
	s_mov_b32 m0, s35
	ds_read_b128 v[182:185], v148 offset:16384
	ds_read_b128 v[186:189], v148 offset:17408
	ds_read_b128 v[190:193], v148 offset:18432
	ds_read_b128 v[194:197], v148 offset:19456
	ds_read_b128 v[198:201], v148 offset:20480
	ds_read_b128 v[202:205], v148 offset:21504
	ds_read_b128 v[206:209], v148 offset:22528
	ds_read_b128 v[210:213], v148 offset:23552
	global_load_lds_dwordx4 v[142:143], off
	s_add_i32 m0, s35, 0x2000
	s_add_u32 s80, s10, 0x80000
	v_lshl_add_u64 v[214:215], s[10:11], 0, v[134:135]
	s_addc_u32 s81, s11, 0
	s_add_i32 s35, s54, s24
	global_load_lds_dwordx4 v[214:215], off
	v_lshl_add_u64 v[216:217], s[80:81], 0, v[128:129]
	s_mov_b32 m0, s35
	v_lshl_add_u64 v[218:219], s[12:13], 0, v[132:133]
	global_load_lds_dwordx4 v[216:217], off
	v_lshl_add_u64 v[216:217], s[80:81], 0, v[134:135]
	s_add_i32 m0, s35, 0x2000
	s_nop 0
	global_load_lds_dwordx4 v[216:217], off
	v_lshl_add_u64 v[216:217], s[12:13], 0, v[130:131]
	s_mov_b32 m0, s25
	s_nop 0
	global_load_lds_dwordx4 v[216:217], off
	s_mov_b32 m0, s26
	s_nop 0
	global_load_lds_dwordx4 v[218:219], off
	s_waitcnt vmcnt(8)
	s_waitcnt lgkmcnt(0)
	s_barrier
; #define PG8_STAGE(bufoff, gbase, voff) do { _Pragma("unroll") for (int _i = 0; _i < 2; ++_i) \
;         __builtin_amdgcn_global_load_lds((const unsigned*)((const char*)(gbase) + (voff)[_i]), (PG8_LAS unsigned*)(lds + (bufoff) + ldsw + _i * 8192), 16, 0, 0); } while (0)
; #define PG8_LDA(dst, b, h) do { _Pragma("unroll") for (int m = 0; m < 4; ++m) _Pragma("unroll") for (int k = 0; k < 2; ++k) dst[m][k] = *(const PG8_LAS bf16x8*)(lds + PG8_SA(b, h) + aoff + m * 2048 + k * 1024); } while (0)
; #define PG8_LDB(dst, b, h) do { _Pragma("unroll") for (int n = 0; n < 2; ++n) _Pragma("unroll") for (int k = 0; k < 2; ++k) dst[n][k] = *(const PG8_LAS bf16x8*)(lds + PG8_SB(b, h) + boff + n * 2048 + k * 1024); } while (0)
; #define PG8_MMA(ai, bj, At, Bt) do { __builtin_amdgcn_s_setprio(1); _Pragma("unroll") for (int m = 0; m < 4; ++m) _Pragma("unroll") for (int n = 0; n < 2; ++n) _Pragma("unroll") for (int k = 0; k < 2; ++k) \
;         acc[ai][bj][m][n] = __builtin_amdgcn_mfma_f32_16x16x32_bf16(Bt[n][k], At[m][k], acc[ai][bj][m][n], 0, 0, 0); __builtin_amdgcn_s_setprio(0); } while (0)
; #define PG8_WAIT_V(n) asm volatile("s_waitcnt vmcnt(" #n ")" ::: "memory")
; #define PG8_WAIT_L(n) asm volatile("s_waitcnt lgkmcnt(" #n ")" ::: "memory")
; #define PG8_BAR __builtin_amdgcn_s_barrier()
; #define PG8_SCHED __builtin_amdgcn_sched_barrier(0)
; template <class Epi, class Sched, bool ALIGN_EPI = false, bool SP2 = false>
; __device__ __forceinline__ void gemm_phase(PG8_LAS unsigned char* lds, const Gemm g, const Sched& S, const Epi& E) {
;     ...
;             PG8_WAIT_V(8); PG8_WAIT_L(0); PG8_BAR; PG8_MMA(1, 0, At, B0); PG8_MMA(1, 1, At, B1); PG8_BAR; PG8_SCHED;
;             PG8_LDB(B0, 1, 0); PG8_LDB(B1, 1, 1); PG8_SCHED; PG8_LDA(At, 1, 0); PG8_STAGE(PG8_SA(0, 1), a2 + hstep, voffA);
;             PG8_WAIT_V(8); PG8_WAIT_L(0); PG8_BAR; PG8_MMA(0, 0, At, B0); PG8_MMA(0, 1, At, B1); PG8_BAR; PG8_SCHED;
	s_waitcnt lgkmcnt(0)
	v_mfma_f32_16x16x32_bf16 v[60:63], v[150:153], v[182:185], v[60:63]
	v_mfma_f32_16x16x32_bf16 v[56:59], v[158:161], v[182:185], v[56:59]
	v_mfma_f32_16x16x32_bf16 v[44:47], v[150:153], v[190:193], v[44:47]
	v_mfma_f32_16x16x32_bf16 v[40:43], v[158:161], v[190:193], v[40:43]
	v_mfma_f32_16x16x32_bf16 v[28:31], v[150:153], v[198:201], v[28:31]
	v_mfma_f32_16x16x32_bf16 v[24:27], v[158:161], v[198:201], v[24:27]
	v_mfma_f32_16x16x32_bf16 v[12:15], v[150:153], v[206:209], v[12:15]
	v_mfma_f32_16x16x32_bf16 v[8:11], v[158:161], v[206:209], v[8:11]
	v_mfma_f32_16x16x32_bf16 v[60:63], v[154:157], v[186:189], v[60:63]
	v_mfma_f32_16x16x32_bf16 v[56:59], v[162:165], v[186:189], v[56:59]
	v_mfma_f32_16x16x32_bf16 v[44:47], v[154:157], v[194:197], v[44:47]
	v_mfma_f32_16x16x32_bf16 v[40:43], v[162:165], v[194:197], v[40:43]
	v_mfma_f32_16x16x32_bf16 v[28:31], v[154:157], v[202:205], v[28:31]
	v_mfma_f32_16x16x32_bf16 v[24:27], v[162:165], v[202:205], v[24:27]
	v_mfma_f32_16x16x32_bf16 v[12:15], v[154:157], v[210:213], v[12:15]
	v_mfma_f32_16x16x32_bf16 v[8:11], v[162:165], v[210:213], v[8:11]
	v_mfma_f32_16x16x32_bf16 v[52:55], v[166:169], v[182:185], v[52:55]
	v_mfma_f32_16x16x32_bf16 v[48:51], v[174:177], v[182:185], v[48:51]
	v_mfma_f32_16x16x32_bf16 v[36:39], v[166:169], v[190:193], v[36:39]
	v_mfma_f32_16x16x32_bf16 v[32:35], v[174:177], v[190:193], v[32:35]
	v_mfma_f32_16x16x32_bf16 v[20:23], v[166:169], v[198:201], v[20:23]
	v_mfma_f32_16x16x32_bf16 v[16:19], v[174:177], v[198:201], v[16:19]
	v_mfma_f32_16x16x32_bf16 v[4:7], v[166:169], v[206:209], v[4:7]
	v_mfma_f32_16x16x32_bf16 v[0:3], v[174:177], v[206:209], v[0:3]
	v_mfma_f32_16x16x32_bf16 v[52:55], v[170:173], v[186:189], v[52:55]
	v_mfma_f32_16x16x32_bf16 v[48:51], v[178:181], v[186:189], v[48:51]
	v_mfma_f32_16x16x32_bf16 v[36:39], v[170:173], v[194:197], v[36:39]
	v_mfma_f32_16x16x32_bf16 v[32:35], v[178:181], v[194:197], v[32:35]
	v_mfma_f32_16x16x32_bf16 v[20:23], v[170:173], v[202:205], v[20:23]
	v_mfma_f32_16x16x32_bf16 v[16:19], v[178:181], v[202:205], v[16:19]
	v_mfma_f32_16x16x32_bf16 v[4:7], v[170:173], v[210:213], v[4:7]
	v_mfma_f32_16x16x32_bf16 v[0:3], v[178:181], v[210:213], v[0:3]
	s_barrier
	s_add_i32 s35, 0, 0x18000
	v_add_u32_e32 v149, s35, v146
	s_add_i32 s54, 0, 0x1c000
	ds_read_b128 v[150:153], v149
	ds_read_b128 v[154:157], v149 offset:1024
	ds_read_b128 v[158:161], v149 offset:2048
	ds_read_b128 v[162:165], v149 offset:3072
	v_add_u32_e32 v149, s54, v146
	ds_read_b128 v[166:169], v149
	ds_read_b128 v[170:173], v149 offset:1024
	ds_read_b128 v[174:177], v149 offset:2048
	ds_read_b128 v[178:181], v149 offset:3072
	s_add_u32 s12, s12, 0x80000
	s_addc_u32 s13, s13, 0
	s_mov_b32 m0, s27
	v_lshl_add_u64 v[220:221], s[12:13], 0, v[130:131]
	ds_read_b128 v[182:185], v148 offset:32768
	ds_read_b128 v[186:189], v148 offset:33792
	ds_read_b128 v[190:193], v148 offset:34816
	ds_read_b128 v[194:197], v148 offset:35840
	ds_read_b128 v[198:201], v148 offset:36864
	ds_read_b128 v[202:205], v148 offset:37888
	ds_read_b128 v[206:209], v148 offset:38912
	ds_read_b128 v[210:213], v148 offset:39936
	global_load_lds_dwordx4 v[220:221], off
	v_lshl_add_u64 v[220:221], s[12:13], 0, v[132:133]
	s_mov_b32 m0, s28
	s_nop 0
	global_load_lds_dwordx4 v[220:221], off
	s_waitcnt vmcnt(8)
	s_waitcnt lgkmcnt(0)
	s_barrier
	s_waitcnt lgkmcnt(0)
	v_mfma_f32_16x16x32_bf16 v[124:127], v[150:153], v[182:185], v[124:127]
	v_mfma_f32_16x16x32_bf16 v[120:123], v[158:161], v[182:185], v[120:123]
	v_mfma_f32_16x16x32_bf16 v[108:111], v[150:153], v[190:193], v[108:111]
	v_mfma_f32_16x16x32_bf16 v[104:107], v[158:161], v[190:193], v[104:107]
	v_mfma_f32_16x16x32_bf16 v[92:95], v[150:153], v[198:201], v[92:95]
	v_mfma_f32_16x16x32_bf16 v[88:91], v[158:161], v[198:201], v[88:91]
	v_mfma_f32_16x16x32_bf16 v[76:79], v[150:153], v[206:209], v[76:79]
	v_mfma_f32_16x16x32_bf16 v[72:75], v[158:161], v[206:209], v[72:75]
	v_mfma_f32_16x16x32_bf16 v[124:127], v[154:157], v[186:189], v[124:127]
	v_mfma_f32_16x16x32_bf16 v[120:123], v[162:165], v[186:189], v[120:123]
	v_mfma_f32_16x16x32_bf16 v[108:111], v[154:157], v[194:197], v[108:111]
	v_mfma_f32_16x16x32_bf16 v[104:107], v[162:165], v[194:197], v[104:107]
	v_mfma_f32_16x16x32_bf16 v[92:95], v[154:157], v[202:205], v[92:95]
	v_mfma_f32_16x16x32_bf16 v[88:91], v[162:165], v[202:205], v[88:91]
	v_mfma_f32_16x16x32_bf16 v[76:79], v[154:157], v[210:213], v[76:79]
	v_mfma_f32_16x16x32_bf16 v[72:75], v[162:165], v[210:213], v[72:75]
	v_mfma_f32_16x16x32_bf16 v[116:119], v[166:169], v[182:185], v[116:119]
	v_mfma_f32_16x16x32_bf16 v[112:115], v[174:177], v[182:185], v[112:115]
	v_mfma_f32_16x16x32_bf16 v[100:103], v[166:169], v[190:193], v[100:103]
	v_mfma_f32_16x16x32_bf16 v[96:99], v[174:177], v[190:193], v[96:99]
	v_mfma_f32_16x16x32_bf16 v[84:87], v[166:169], v[198:201], v[84:87]
	v_mfma_f32_16x16x32_bf16 v[80:83], v[174:177], v[198:201], v[80:83]
	v_mfma_f32_16x16x32_bf16 v[68:71], v[166:169], v[206:209], v[68:71]
	v_mfma_f32_16x16x32_bf16 v[64:67], v[174:177], v[206:209], v[64:67]
	v_mfma_f32_16x16x32_bf16 v[116:119], v[170:173], v[186:189], v[116:119]
	v_mfma_f32_16x16x32_bf16 v[112:115], v[178:181], v[186:189], v[112:115]
	v_mfma_f32_16x16x32_bf16 v[100:103], v[170:173], v[194:197], v[100:103]
	v_mfma_f32_16x16x32_bf16 v[96:99], v[178:181], v[194:197], v[96:99]
	v_mfma_f32_16x16x32_bf16 v[84:87], v[170:173], v[202:205], v[84:87]
	v_mfma_f32_16x16x32_bf16 v[80:83], v[178:181], v[202:205], v[80:83]
	v_mfma_f32_16x16x32_bf16 v[68:71], v[170:173], v[210:213], v[68:71]
	v_mfma_f32_16x16x32_bf16 v[64:67], v[178:181], v[210:213], v[64:67]
	s_barrier
; #define PG8_STAGE(bufoff, gbase, voff) do { _Pragma("unroll") for (int _i = 0; _i < 2; ++_i) \
;         __builtin_amdgcn_global_load_lds((const unsigned*)((const char*)(gbase) + (voff)[_i]), (PG8_LAS unsigned*)(lds + (bufoff) + ldsw + _i * 8192), 16, 0, 0); } while (0)
; #define PG8_LDA(dst, b, h) do { _Pragma("unroll") for (int m = 0; m < 4; ++m) _Pragma("unroll") for (int k = 0; k < 2; ++k) dst[m][k] = *(const PG8_LAS bf16x8*)(lds + PG8_SA(b, h) + aoff + m * 2048 + k * 1024); } while (0)
; #define PG8_MMA(ai, bj, At, Bt) do { __builtin_amdgcn_s_setprio(1); _Pragma("unroll") for (int m = 0; m < 4; ++m) _Pragma("unroll") for (int n = 0; n < 2; ++n) _Pragma("unroll") for (int k = 0; k < 2; ++k) \
;         acc[ai][bj][m][n] = __builtin_amdgcn_mfma_f32_16x16x32_bf16(Bt[n][k], At[m][k], acc[ai][bj][m][n], 0, 0, 0); __builtin_amdgcn_s_setprio(0); } while (0)
; #define PG8_WAIT_V(n) asm volatile("s_waitcnt vmcnt(" #n ")" ::: "memory")
; #define PG8_WAIT_L(n) asm volatile("s_waitcnt lgkmcnt(" #n ")" ::: "memory")
; #define PG8_BAR __builtin_amdgcn_s_barrier()
; #define PG8_SCHED __builtin_amdgcn_sched_barrier(0)
; template <class Epi, class Sched, bool ALIGN_EPI = false, bool SP2 = false>
; __device__ __forceinline__ void gemm_phase(PG8_LAS unsigned char* lds, const Gemm g, const Sched& S, const Epi& E) {
;     ...
;             PG8_LDA(At, 1, 1); PG8_STAGE(PG8_SB(1, 0), b3, voffB); PG8_STAGE(PG8_SB(1, 1), b3 + hstep, voffB); PG8_STAGE(PG8_SA(1, 0), a3, voffA);
;             PG8_WAIT_V(8); PG8_WAIT_L(0); PG8_BAR; PG8_MMA(1, 0, At, B0); PG8_MMA(1, 1, At, B1); PG8_BAR; PG8_SCHED;
	s_add_i32 s12, s35, s24
	v_lshl_add_u64 v[142:143], v[142:143], 0, s[84:85]
	s_mov_b32 m0, s12
	ds_read_b128 v[182:185], v148 offset:49152
	ds_read_b128 v[186:189], v148 offset:50176
	ds_read_b128 v[190:193], v148 offset:51200
	ds_read_b128 v[194:197], v148 offset:52224
	ds_read_b128 v[198:201], v148 offset:53248
	ds_read_b128 v[202:205], v148 offset:54272
	ds_read_b128 v[206:209], v148 offset:55296
	ds_read_b128 v[210:213], v148 offset:56320
	global_load_lds_dwordx4 v[142:143], off
	s_add_i32 m0, s12, 0x2000
	s_add_u32 s10, s10, 0x80080
	v_lshl_add_u64 v[142:143], v[214:215], 0, s[84:85]
	s_addc_u32 s11, s11, 0
	s_add_i32 s12, s54, s24
	global_load_lds_dwordx4 v[142:143], off
	v_lshl_add_u64 v[142:143], s[10:11], 0, v[128:129]
	s_mov_b32 m0, s12
	s_nop 0
	global_load_lds_dwordx4 v[142:143], off
	v_lshl_add_u64 v[142:143], s[10:11], 0, v[134:135]
	s_add_i32 m0, s12, 0x2000
	s_nop 0
	global_load_lds_dwordx4 v[142:143], off
	v_lshl_add_u64 v[142:143], v[216:217], 0, s[84:85]
	s_mov_b32 m0, s29
	s_nop 0
	global_load_lds_dwordx4 v[142:143], off
	v_lshl_add_u64 v[142:143], v[218:219], 0, s[84:85]
	s_mov_b32 m0, s90
	s_nop 0
	global_load_lds_dwordx4 v[142:143], off
	s_waitcnt vmcnt(8)
	s_waitcnt lgkmcnt(0)
	s_barrier
	s_waitcnt lgkmcnt(0)
	v_mfma_f32_16x16x32_bf16 v[60:63], v[150:153], v[182:185], v[60:63]
	v_mfma_f32_16x16x32_bf16 v[56:59], v[158:161], v[182:185], v[56:59]
	v_mfma_f32_16x16x32_bf16 v[44:47], v[150:153], v[190:193], v[44:47]
	v_mfma_f32_16x16x32_bf16 v[40:43], v[158:161], v[190:193], v[40:43]
	v_mfma_f32_16x16x32_bf16 v[28:31], v[150:153], v[198:201], v[28:31]
	v_mfma_f32_16x16x32_bf16 v[24:27], v[158:161], v[198:201], v[24:27]
	v_mfma_f32_16x16x32_bf16 v[12:15], v[150:153], v[206:209], v[12:15]
	v_mfma_f32_16x16x32_bf16 v[8:11], v[158:161], v[206:209], v[8:11]
	v_mfma_f32_16x16x32_bf16 v[60:63], v[154:157], v[186:189], v[60:63]
	v_mfma_f32_16x16x32_bf16 v[56:59], v[162:165], v[186:189], v[56:59]
	v_mfma_f32_16x16x32_bf16 v[44:47], v[154:157], v[194:197], v[44:47]
	v_mfma_f32_16x16x32_bf16 v[40:43], v[162:165], v[194:197], v[40:43]
	v_mfma_f32_16x16x32_bf16 v[28:31], v[154:157], v[202:205], v[28:31]
	v_mfma_f32_16x16x32_bf16 v[24:27], v[162:165], v[202:205], v[24:27]
	v_mfma_f32_16x16x32_bf16 v[12:15], v[154:157], v[210:213], v[12:15]
	v_mfma_f32_16x16x32_bf16 v[8:11], v[162:165], v[210:213], v[8:11]
	v_mfma_f32_16x16x32_bf16 v[52:55], v[166:169], v[182:185], v[52:55]
	v_mfma_f32_16x16x32_bf16 v[48:51], v[174:177], v[182:185], v[48:51]
	v_mfma_f32_16x16x32_bf16 v[36:39], v[166:169], v[190:193], v[36:39]
	v_mfma_f32_16x16x32_bf16 v[32:35], v[174:177], v[190:193], v[32:35]
	v_mfma_f32_16x16x32_bf16 v[20:23], v[166:169], v[198:201], v[20:23]
	v_mfma_f32_16x16x32_bf16 v[16:19], v[174:177], v[198:201], v[16:19]
	v_mfma_f32_16x16x32_bf16 v[4:7], v[166:169], v[206:209], v[4:7]
	v_mfma_f32_16x16x32_bf16 v[0:3], v[174:177], v[206:209], v[0:3]
	v_mfma_f32_16x16x32_bf16 v[52:55], v[170:173], v[186:189], v[52:55]
	v_mfma_f32_16x16x32_bf16 v[48:51], v[178:181], v[186:189], v[48:51]
	v_mfma_f32_16x16x32_bf16 v[36:39], v[170:173], v[194:197], v[36:39]
	v_mfma_f32_16x16x32_bf16 v[32:35], v[178:181], v[194:197], v[32:35]
	v_mfma_f32_16x16x32_bf16 v[20:23], v[170:173], v[202:205], v[20:23]
	v_mfma_f32_16x16x32_bf16 v[16:19], v[178:181], v[202:205], v[16:19]
	v_mfma_f32_16x16x32_bf16 v[4:7], v[170:173], v[210:213], v[4:7]
	v_mfma_f32_16x16x32_bf16 v[0:3], v[178:181], v[210:213], v[0:3]
	s_barrier
	s_add_i32 s34, s34, 2
	s_add_u32 s8, s8, 0x100
	s_addc_u32 s9, s9, 0
	s_add_u32 vcc_lo, vcc_lo, 0x100
	s_addc_u32 vcc_hi, vcc_hi, 0
	s_cmp_gt_u32 s34, 29
	s_cbranch_scc0 .LBB0_704
	s_and_b64 vcc, exec, s[4:5]
	s_cbranch_vccz .LBB0_707
	s_barrier

; #define PG8_STAGE(bufoff, gbase, voff) do { _Pragma("unroll") for (int _i = 0; _i < 2; ++_i) \
;         __builtin_amdgcn_global_load_lds((const unsigned*)((const char*)(gbase) + (voff)[_i]), (PG8_LAS unsigned*)(lds + (bufoff) + ldsw + _i * 8192), 16, 0, 0); } while (0)
; #define PG8_LDA(dst, b, h) do { _Pragma("unroll") for (int m = 0; m < 4; ++m) _Pragma("unroll") for (int k = 0; k < 2; ++k) dst[m][k] = *(const PG8_LAS bf16x8*)(lds + PG8_SA(b, h) + aoff + m * 2048 + k * 1024); } while (0)
; #define PG8_LDB(dst, b, h) do { _Pragma("unroll") for (int n = 0; n < 2; ++n) _Pragma("unroll") for (int k = 0; k < 2; ++k) dst[n][k] = *(const PG8_LAS bf16x8*)(lds + PG8_SB(b, h) + boff + n * 2048 + k * 1024); } while (0)
; #define PG8_MMA(ai, bj, At, Bt) do { __builtin_amdgcn_s_setprio(1); _Pragma("unroll") for (int m = 0; m < 4; ++m) _Pragma("unroll") for (int n = 0; n < 2; ++n) _Pragma("unroll") for (int k = 0; k < 2; ++k) \
;         acc[ai][bj][m][n] = __builtin_amdgcn_mfma_f32_16x16x32_bf16(Bt[n][k], At[m][k], acc[ai][bj][m][n], 0, 0, 0); __builtin_amdgcn_s_setprio(0); } while (0)
; #define PG8_WAIT_V(n) asm volatile("s_waitcnt vmcnt(" #n ")" ::: "memory")
; #define PG8_WAIT_L(n) asm volatile("s_waitcnt lgkmcnt(" #n ")" ::: "memory")
; template <class Epi, class Sched, bool ALIGN_EPI = false, bool SP2 = false>
; __device__ __forceinline__ void gemm_phase(PG8_LAS unsigned char* lds, const Gemm g, const Sched& S, const Epi& E) {
;     ...
;             const bool last = (t == nt - 2);
;             const char* a1 = cA + (size_t)(t + 1) * kstep;
;             const char* a2 = last ? nA : cA + (size_t)(t + 2) * kstep; const char* b2 = last ? nB : cB + (size_t)(t + 2) * kstep;
;             const char* a3 = a2 + kstep; const char* b3 = b2 + kstep;
;             if (last && has_next) S.a_ready(nxt);
;             if constexpr (SP2) {
;             PG8_LDB(B0, 0, 0); PG8_LDB(B1, 0, 1); PG8_SCHED; PG8_LDA(At, 0, 0); PG8_STAGE(PG8_SA(1, 1), a1 + hstep, voffA);
;             PG8_WAIT_V(8); PG8_WAIT_L(0); PG8_BAR; PG8_MMA(0, 0, At, B0); PG8_MMA(0, 1, At, B1); PG8_BAR; PG8_SCHED;
;             PG8_LDA(At, 0, 1); PG8_STAGE(PG8_SB(0, 0), b2, voffB); PG8_STAGE(PG8_SB(0, 1), b2 + hstep, voffB); PG8_STAGE(PG8_SA(0, 0), a2, voffA);
;             PG8_WAIT_V(8); PG8_WAIT_L(0); PG8_BAR; PG8_MMA(1, 0, At, B0); PG8_MMA(1, 1, At, B1); PG8_BAR; PG8_SCHED;
.LBB0_783:
	s_add_u32 vcc_lo, s38, 0x100
	s_addc_u32 vcc_hi, s39, 0
	s_add_i32 s54, 0, 0x10000
	s_cmpk_eq_i32 s35, 0x7c
	s_cselect_b32 s15, s1, vcc_hi
	s_cselect_b32 s14, s9, vcc_lo
	v_add_u32_e32 v140, s54, v143
	s_cselect_b32 s5, s7, s34
	s_cselect_b32 s4, s30, s31
	s_add_i32 s80, 0, 0x14000
	ds_read_b128 v[136:139], v140
	ds_read_b128 v[148:151], v140 offset:1024
	ds_read_b128 v[152:155], v140 offset:2048
	ds_read_b128 v[156:159], v140 offset:3072
	v_add_u32_e32 v140, s80, v143
	ds_read_b128 v[160:163], v140
	ds_read_b128 v[164:167], v140 offset:1024
	ds_read_b128 v[168:171], v140 offset:2048
	ds_read_b128 v[172:175], v140 offset:3072
	v_lshl_add_u64 v[140:141], s[38:39], 0, v[132:133]
	s_add_i32 m0, s91, 0xc000
	ds_read_b128 v[176:179], v146
	ds_read_b128 v[180:183], v146 offset:1024
	ds_read_b128 v[184:187], v146 offset:2048
	ds_read_b128 v[188:191], v146 offset:3072
	ds_read_b128 v[192:195], v146 offset:4096
	ds_read_b128 v[196:199], v146 offset:5120
	ds_read_b128 v[200:203], v146 offset:6144
	ds_read_b128 v[204:207], v146 offset:7168
	global_load_lds_dwordx4 v[140:141], off
	v_lshl_add_u64 v[140:141], s[38:39], 0, v[134:135]
	s_add_i32 m0, s91, 0xe000
	s_nop 0
	global_load_lds_dwordx4 v[140:141], off
	s_waitcnt vmcnt(8)
	s_waitcnt lgkmcnt(0)
	s_barrier
	s_waitcnt lgkmcnt(0)
	v_mfma_f32_16x16x32_bf16 v[124:127], v[136:139], v[176:179], v[124:127]
	v_mfma_f32_16x16x32_bf16 v[120:123], v[152:155], v[176:179], v[120:123]
	v_mfma_f32_16x16x32_bf16 v[108:111], v[136:139], v[184:187], v[108:111]
	v_mfma_f32_16x16x32_bf16 v[104:107], v[152:155], v[184:187], v[104:107]
	v_mfma_f32_16x16x32_bf16 v[92:95], v[136:139], v[192:195], v[92:95]
	v_mfma_f32_16x16x32_bf16 v[88:91], v[152:155], v[192:195], v[88:91]
	v_mfma_f32_16x16x32_bf16 v[76:79], v[136:139], v[200:203], v[76:79]
	v_mfma_f32_16x16x32_bf16 v[72:75], v[152:155], v[200:203], v[72:75]
	v_mfma_f32_16x16x32_bf16 v[124:127], v[148:151], v[180:183], v[124:127]
	v_mfma_f32_16x16x32_bf16 v[120:123], v[156:159], v[180:183], v[120:123]
	v_mfma_f32_16x16x32_bf16 v[108:111], v[148:151], v[188:191], v[108:111]
	v_mfma_f32_16x16x32_bf16 v[104:107], v[156:159], v[188:191], v[104:107]
	v_mfma_f32_16x16x32_bf16 v[92:95], v[148:151], v[196:199], v[92:95]
	v_mfma_f32_16x16x32_bf16 v[88:91], v[156:159], v[196:199], v[88:91]
	v_mfma_f32_16x16x32_bf16 v[76:79], v[148:151], v[204:207], v[76:79]
	v_mfma_f32_16x16x32_bf16 v[72:75], v[156:159], v[204:207], v[72:75]
	v_mfma_f32_16x16x32_bf16 v[116:119], v[160:163], v[176:179], v[116:119]
	v_mfma_f32_16x16x32_bf16 v[112:115], v[168:171], v[176:179], v[112:115]
	v_mfma_f32_16x16x32_bf16 v[100:103], v[160:163], v[184:187], v[100:103]
	v_mfma_f32_16x16x32_bf16 v[96:99], v[168:171], v[184:187], v[96:99]
	v_mfma_f32_16x16x32_bf16 v[84:87], v[160:163], v[192:195], v[84:87]
	v_mfma_f32_16x16x32_bf16 v[80:83], v[168:171], v[192:195], v[80:83]
	v_mfma_f32_16x16x32_bf16 v[68:71], v[160:163], v[200:203], v[68:71]
	v_mfma_f32_16x16x32_bf16 v[64:67], v[168:171], v[200:203], v[64:67]
	v_mfma_f32_16x16x32_bf16 v[116:119], v[164:167], v[180:183], v[116:119]
	v_mfma_f32_16x16x32_bf16 v[112:115], v[172:175], v[180:183], v[112:115]
	v_mfma_f32_16x16x32_bf16 v[100:103], v[164:167], v[188:191], v[100:103]
	v_mfma_f32_16x16x32_bf16 v[96:99], v[172:175], v[188:191], v[96:99]
	v_mfma_f32_16x16x32_bf16 v[84:87], v[164:167], v[196:199], v[84:87]
	v_mfma_f32_16x16x32_bf16 v[80:83], v[172:175], v[196:199], v[80:83]
	v_mfma_f32_16x16x32_bf16 v[68:71], v[164:167], v[204:207], v[68:71]
	v_mfma_f32_16x16x32_bf16 v[64:67], v[172:175], v[204:207], v[64:67]
	s_barrier
	s_add_i32 s38, s54, s23
	v_lshl_add_u64 v[140:141], s[4:5], 0, v[128:129]
	s_mov_b32 m0, s38
	ds_read_b128 v[176:179], v146 offset:16384
	ds_read_b128 v[180:183], v146 offset:17408
	ds_read_b128 v[184:187], v146 offset:18432
	ds_read_b128 v[188:191], v146 offset:19456
	ds_read_b128 v[192:195], v146 offset:20480
	ds_read_b128 v[196:199], v146 offset:21504
	ds_read_b128 v[200:203], v146 offset:22528
	ds_read_b128 v[204:207], v146 offset:23552
	global_load_lds_dwordx4 v[140:141], off
	s_add_i32 m0, s38, 0x2000
	s_add_u32 s38, s4, 0x200000
	v_lshl_add_u64 v[208:209], s[4:5], 0, v[130:131]
	s_addc_u32 s39, s5, 0
	s_add_i32 s54, s80, s23
	global_load_lds_dwordx4 v[208:209], off
	v_lshl_add_u64 v[210:211], s[38:39], 0, v[128:129]
	s_mov_b32 m0, s54
	v_lshl_add_u64 v[212:213], s[14:15], 0, v[130:131]
	global_load_lds_dwordx4 v[210:211], off
	v_lshl_add_u64 v[210:211], s[38:39], 0, v[130:131]
	s_add_i32 m0, s54, 0x2000
	s_nop 0
	global_load_lds_dwordx4 v[210:211], off
	v_lshl_add_u64 v[210:211], s[14:15], 0, v[128:129]
	s_mov_b32 m0, s91
	s_nop 0
	global_load_lds_dwordx4 v[210:211], off
	s_mov_b32 m0, s24
	s_nop 0
	global_load_lds_dwordx4 v[212:213], off
	s_waitcnt vmcnt(8)
	s_waitcnt lgkmcnt(0)
	s_barrier
; #define PG8_STAGE(bufoff, gbase, voff) do { _Pragma("unroll") for (int _i = 0; _i < 2; ++_i) \
;         __builtin_amdgcn_global_load_lds((const unsigned*)((const char*)(gbase) + (voff)[_i]), (PG8_LAS unsigned*)(lds + (bufoff) + ldsw + _i * 8192), 16, 0, 0); } while (0)
; #define PG8_LDA(dst, b, h) do { _Pragma("unroll") for (int m = 0; m < 4; ++m) _Pragma("unroll") for (int k = 0; k < 2; ++k) dst[m][k] = *(const PG8_LAS bf16x8*)(lds + PG8_SA(b, h) + aoff + m * 2048 + k * 1024); } while (0)
; #define PG8_LDB(dst, b, h) do { _Pragma("unroll") for (int n = 0; n < 2; ++n) _Pragma("unroll") for (int k = 0; k < 2; ++k) dst[n][k] = *(const PG8_LAS bf16x8*)(lds + PG8_SB(b, h) + boff + n * 2048 + k * 1024); } while (0)
; #define PG8_MMA(ai, bj, At, Bt) do { __builtin_amdgcn_s_setprio(1); _Pragma("unroll") for (int m = 0; m < 4; ++m) _Pragma("unroll") for (int n = 0; n < 2; ++n) _Pragma("unroll") for (int k = 0; k < 2; ++k) \
;         acc[ai][bj][m][n] = __builtin_amdgcn_mfma_f32_16x16x32_bf16(Bt[n][k], At[m][k], acc[ai][bj][m][n], 0, 0, 0); __builtin_amdgcn_s_setprio(0); } while (0)
; #define PG8_WAIT_V(n) asm volatile("s_waitcnt vmcnt(" #n ")" ::: "memory")
; #define PG8_WAIT_L(n) asm volatile("s_waitcnt lgkmcnt(" #n ")" ::: "memory")
; #define PG8_BAR __builtin_amdgcn_s_barrier()
; #define PG8_SCHED __builtin_amdgcn_sched_barrier(0)
; template <class Epi, class Sched, bool ALIGN_EPI = false, bool SP2 = false>
; __device__ __forceinline__ void gemm_phase(PG8_LAS unsigned char* lds, const Gemm g, const Sched& S, const Epi& E) {
;     ...
;             PG8_WAIT_V(8); PG8_WAIT_L(0); PG8_BAR; PG8_MMA(1, 0, At, B0); PG8_MMA(1, 1, At, B1); PG8_BAR; PG8_SCHED;
;             PG8_LDB(B0, 1, 0); PG8_LDB(B1, 1, 1); PG8_SCHED; PG8_LDA(At, 1, 0); PG8_STAGE(PG8_SA(0, 1), a2 + hstep, voffA);
;             PG8_WAIT_V(8); PG8_WAIT_L(0); PG8_BAR; PG8_MMA(0, 0, At, B0); PG8_MMA(0, 1, At, B1); PG8_BAR; PG8_SCHED;
	s_waitcnt lgkmcnt(0)
	v_mfma_f32_16x16x32_bf16 v[60:63], v[136:139], v[176:179], v[60:63]
	v_mfma_f32_16x16x32_bf16 v[56:59], v[152:155], v[176:179], v[56:59]
	v_mfma_f32_16x16x32_bf16 v[44:47], v[136:139], v[184:187], v[44:47]
	v_mfma_f32_16x16x32_bf16 v[40:43], v[152:155], v[184:187], v[40:43]
	v_mfma_f32_16x16x32_bf16 v[28:31], v[136:139], v[192:195], v[28:31]
	v_mfma_f32_16x16x32_bf16 v[24:27], v[152:155], v[192:195], v[24:27]
	v_mfma_f32_16x16x32_bf16 v[12:15], v[136:139], v[200:203], v[12:15]
	v_mfma_f32_16x16x32_bf16 v[8:11], v[152:155], v[200:203], v[8:11]
	v_mfma_f32_16x16x32_bf16 v[60:63], v[148:151], v[180:183], v[60:63]
	v_mfma_f32_16x16x32_bf16 v[56:59], v[156:159], v[180:183], v[56:59]
	v_mfma_f32_16x16x32_bf16 v[44:47], v[148:151], v[188:191], v[44:47]
	v_mfma_f32_16x16x32_bf16 v[40:43], v[156:159], v[188:191], v[40:43]
	v_mfma_f32_16x16x32_bf16 v[28:31], v[148:151], v[196:199], v[28:31]
	v_mfma_f32_16x16x32_bf16 v[24:27], v[156:159], v[196:199], v[24:27]
	v_mfma_f32_16x16x32_bf16 v[12:15], v[148:151], v[204:207], v[12:15]
	v_mfma_f32_16x16x32_bf16 v[8:11], v[156:159], v[204:207], v[8:11]
	v_mfma_f32_16x16x32_bf16 v[52:55], v[160:163], v[176:179], v[52:55]
	v_mfma_f32_16x16x32_bf16 v[48:51], v[168:171], v[176:179], v[48:51]
	v_mfma_f32_16x16x32_bf16 v[36:39], v[160:163], v[184:187], v[36:39]
	v_mfma_f32_16x16x32_bf16 v[32:35], v[168:171], v[184:187], v[32:35]
	v_mfma_f32_16x16x32_bf16 v[20:23], v[160:163], v[192:195], v[20:23]
	v_mfma_f32_16x16x32_bf16 v[16:19], v[168:171], v[192:195], v[16:19]
	v_mfma_f32_16x16x32_bf16 v[4:7], v[160:163], v[200:203], v[4:7]
	v_mfma_f32_16x16x32_bf16 v[0:3], v[168:171], v[200:203], v[0:3]
	v_mfma_f32_16x16x32_bf16 v[52:55], v[164:167], v[180:183], v[52:55]
	v_mfma_f32_16x16x32_bf16 v[48:51], v[172:175], v[180:183], v[48:51]
	v_mfma_f32_16x16x32_bf16 v[36:39], v[164:167], v[188:191], v[36:39]
	v_mfma_f32_16x16x32_bf16 v[32:35], v[172:175], v[188:191], v[32:35]
	v_mfma_f32_16x16x32_bf16 v[20:23], v[164:167], v[196:199], v[20:23]
	v_mfma_f32_16x16x32_bf16 v[16:19], v[172:175], v[196:199], v[16:19]
	v_mfma_f32_16x16x32_bf16 v[4:7], v[164:167], v[204:207], v[4:7]
	v_mfma_f32_16x16x32_bf16 v[0:3], v[172:175], v[204:207], v[0:3]
	s_barrier
	s_add_i32 s38, 0, 0x18000
	v_add_u32_e32 v147, s38, v143
	s_add_i32 s39, 0, 0x1c000
	ds_read_b128 v[136:139], v147
	ds_read_b128 v[148:151], v147 offset:1024
	ds_read_b128 v[152:155], v147 offset:2048
	ds_read_b128 v[156:159], v147 offset:3072
	v_add_u32_e32 v147, s39, v143
	ds_read_b128 v[160:163], v147
	ds_read_b128 v[164:167], v147 offset:1024
	ds_read_b128 v[168:171], v147 offset:2048
	ds_read_b128 v[172:175], v147 offset:3072
	s_add_u32 s14, s14, 0x200000
	s_addc_u32 s15, s15, 0
	s_mov_b32 m0, s25
	v_lshl_add_u64 v[214:215], s[14:15], 0, v[128:129]
	ds_read_b128 v[176:179], v146 offset:32768
	ds_read_b128 v[180:183], v146 offset:33792
	ds_read_b128 v[184:187], v146 offset:34816
	ds_read_b128 v[188:191], v146 offset:35840
	ds_read_b128 v[192:195], v146 offset:36864
	ds_read_b128 v[196:199], v146 offset:37888
	ds_read_b128 v[200:203], v146 offset:38912
	ds_read_b128 v[204:207], v146 offset:39936
	global_load_lds_dwordx4 v[214:215], off
	v_lshl_add_u64 v[214:215], s[14:15], 0, v[130:131]
	s_mov_b32 m0, s26
	s_nop 0
	global_load_lds_dwordx4 v[214:215], off
	s_waitcnt vmcnt(8)
	s_waitcnt lgkmcnt(0)
	s_barrier
	s_waitcnt lgkmcnt(0)
	v_mfma_f32_16x16x32_bf16 v[124:127], v[136:139], v[176:179], v[124:127]
	v_mfma_f32_16x16x32_bf16 v[120:123], v[152:155], v[176:179], v[120:123]
	v_mfma_f32_16x16x32_bf16 v[108:111], v[136:139], v[184:187], v[108:111]
	v_mfma_f32_16x16x32_bf16 v[104:107], v[152:155], v[184:187], v[104:107]
	v_mfma_f32_16x16x32_bf16 v[92:95], v[136:139], v[192:195], v[92:95]
	v_mfma_f32_16x16x32_bf16 v[88:91], v[152:155], v[192:195], v[88:91]
	v_mfma_f32_16x16x32_bf16 v[76:79], v[136:139], v[200:203], v[76:79]
	v_mfma_f32_16x16x32_bf16 v[72:75], v[152:155], v[200:203], v[72:75]
	v_mfma_f32_16x16x32_bf16 v[124:127], v[148:151], v[180:183], v[124:127]
	v_mfma_f32_16x16x32_bf16 v[120:123], v[156:159], v[180:183], v[120:123]
	v_mfma_f32_16x16x32_bf16 v[108:111], v[148:151], v[188:191], v[108:111]
	v_mfma_f32_16x16x32_bf16 v[104:107], v[156:159], v[188:191], v[104:107]
	v_mfma_f32_16x16x32_bf16 v[92:95], v[148:151], v[196:199], v[92:95]
	v_mfma_f32_16x16x32_bf16 v[88:91], v[156:159], v[196:199], v[88:91]
	v_mfma_f32_16x16x32_bf16 v[76:79], v[148:151], v[204:207], v[76:79]
	v_mfma_f32_16x16x32_bf16 v[72:75], v[156:159], v[204:207], v[72:75]
	v_mfma_f32_16x16x32_bf16 v[116:119], v[160:163], v[176:179], v[116:119]
	v_mfma_f32_16x16x32_bf16 v[112:115], v[168:171], v[176:179], v[112:115]
	v_mfma_f32_16x16x32_bf16 v[100:103], v[160:163], v[184:187], v[100:103]
	v_mfma_f32_16x16x32_bf16 v[96:99], v[168:171], v[184:187], v[96:99]
	v_mfma_f32_16x16x32_bf16 v[84:87], v[160:163], v[192:195], v[84:87]
	v_mfma_f32_16x16x32_bf16 v[80:83], v[168:171], v[192:195], v[80:83]
	v_mfma_f32_16x16x32_bf16 v[68:71], v[160:163], v[200:203], v[68:71]
	v_mfma_f32_16x16x32_bf16 v[64:67], v[168:171], v[200:203], v[64:67]
	v_mfma_f32_16x16x32_bf16 v[116:119], v[164:167], v[180:183], v[116:119]
	v_mfma_f32_16x16x32_bf16 v[112:115], v[172:175], v[180:183], v[112:115]
	v_mfma_f32_16x16x32_bf16 v[100:103], v[164:167], v[188:191], v[100:103]
	v_mfma_f32_16x16x32_bf16 v[96:99], v[172:175], v[188:191], v[96:99]
	v_mfma_f32_16x16x32_bf16 v[84:87], v[164:167], v[196:199], v[84:87]
	v_mfma_f32_16x16x32_bf16 v[80:83], v[172:175], v[196:199], v[80:83]
	v_mfma_f32_16x16x32_bf16 v[68:71], v[164:167], v[204:207], v[68:71]
	v_mfma_f32_16x16x32_bf16 v[64:67], v[172:175], v[204:207], v[64:67]
	s_barrier
; #define PG8_STAGE(bufoff, gbase, voff) do { _Pragma("unroll") for (int _i = 0; _i < 2; ++_i) \
;         __builtin_amdgcn_global_load_lds((const unsigned*)((const char*)(gbase) + (voff)[_i]), (PG8_LAS unsigned*)(lds + (bufoff) + ldsw + _i * 8192), 16, 0, 0); } while (0)
; #define PG8_LDA(dst, b, h) do { _Pragma("unroll") for (int m = 0; m < 4; ++m) _Pragma("unroll") for (int k = 0; k < 2; ++k) dst[m][k] = *(const PG8_LAS bf16x8*)(lds + PG8_SA(b, h) + aoff + m * 2048 + k * 1024); } while (0)
; #define PG8_MMA(ai, bj, At, Bt) do { __builtin_amdgcn_s_setprio(1); _Pragma("unroll") for (int m = 0; m < 4; ++m) _Pragma("unroll") for (int n = 0; n < 2; ++n) _Pragma("unroll") for (int k = 0; k < 2; ++k) \
;         acc[ai][bj][m][n] = __builtin_amdgcn_mfma_f32_16x16x32_bf16(Bt[n][k], At[m][k], acc[ai][bj][m][n], 0, 0, 0); __builtin_amdgcn_s_setprio(0); } while (0)
; #define PG8_WAIT_V(n) asm volatile("s_waitcnt vmcnt(" #n ")" ::: "memory")
; #define PG8_WAIT_L(n) asm volatile("s_waitcnt lgkmcnt(" #n ")" ::: "memory")
; #define PG8_BAR __builtin_amdgcn_s_barrier()
; #define PG8_SCHED __builtin_amdgcn_sched_barrier(0)
; template <class Epi, class Sched, bool ALIGN_EPI = false, bool SP2 = false>
; __device__ __forceinline__ void gemm_phase(PG8_LAS unsigned char* lds, const Gemm g, const Sched& S, const Epi& E) {
;     ...
;             PG8_LDA(At, 1, 1); PG8_STAGE(PG8_SB(1, 0), b3, voffB); PG8_STAGE(PG8_SB(1, 1), b3 + hstep, voffB); PG8_STAGE(PG8_SA(1, 0), a3, voffA);
;             PG8_WAIT_V(8); PG8_WAIT_L(0); PG8_BAR; PG8_MMA(1, 0, At, B0); PG8_MMA(1, 1, At, B1); PG8_BAR; PG8_SCHED;
	s_add_i32 s14, s38, s23
	v_lshl_add_u64 v[140:141], v[140:141], 0, s[84:85]
	s_mov_b32 m0, s14
	ds_read_b128 v[176:179], v146 offset:49152
	ds_read_b128 v[180:183], v146 offset:50176
	ds_read_b128 v[184:187], v146 offset:51200
	ds_read_b128 v[188:191], v146 offset:52224
	ds_read_b128 v[192:195], v146 offset:53248
	ds_read_b128 v[196:199], v146 offset:54272
	ds_read_b128 v[200:203], v146 offset:55296
	ds_read_b128 v[204:207], v146 offset:56320
	global_load_lds_dwordx4 v[140:141], off
	s_add_i32 m0, s14, 0x2000
	s_add_u32 s4, s4, 0x200080
	v_lshl_add_u64 v[140:141], v[208:209], 0, s[84:85]
	s_addc_u32 s5, s5, 0
	s_add_i32 s14, s39, s23
	global_load_lds_dwordx4 v[140:141], off
	v_lshl_add_u64 v[140:141], s[4:5], 0, v[128:129]
	s_mov_b32 m0, s14
	s_nop 0
	global_load_lds_dwordx4 v[140:141], off
	v_lshl_add_u64 v[140:141], s[4:5], 0, v[130:131]
	s_add_i32 m0, s14, 0x2000
	s_nop 0
	global_load_lds_dwordx4 v[140:141], off
	v_lshl_add_u64 v[140:141], v[210:211], 0, s[84:85]
	s_mov_b32 m0, s20
	s_nop 0
	global_load_lds_dwordx4 v[140:141], off
	v_lshl_add_u64 v[140:141], v[212:213], 0, s[84:85]
	s_mov_b32 m0, s27
	s_nop 0
	global_load_lds_dwordx4 v[140:141], off
	s_waitcnt vmcnt(8)
	s_waitcnt lgkmcnt(0)
	s_barrier
	s_waitcnt lgkmcnt(0)
	v_mfma_f32_16x16x32_bf16 v[60:63], v[136:139], v[176:179], v[60:63]
	v_mfma_f32_16x16x32_bf16 v[56:59], v[152:155], v[176:179], v[56:59]
	v_mfma_f32_16x16x32_bf16 v[44:47], v[136:139], v[184:187], v[44:47]
	v_mfma_f32_16x16x32_bf16 v[40:43], v[152:155], v[184:187], v[40:43]
	v_mfma_f32_16x16x32_bf16 v[28:31], v[136:139], v[192:195], v[28:31]
	v_mfma_f32_16x16x32_bf16 v[24:27], v[152:155], v[192:195], v[24:27]
	v_mfma_f32_16x16x32_bf16 v[12:15], v[136:139], v[200:203], v[12:15]
	v_mfma_f32_16x16x32_bf16 v[8:11], v[152:155], v[200:203], v[8:11]
	v_mfma_f32_16x16x32_bf16 v[60:63], v[148:151], v[180:183], v[60:63]
	v_mfma_f32_16x16x32_bf16 v[56:59], v[156:159], v[180:183], v[56:59]
	v_mfma_f32_16x16x32_bf16 v[44:47], v[148:151], v[188:191], v[44:47]
	v_mfma_f32_16x16x32_bf16 v[40:43], v[156:159], v[188:191], v[40:43]
	v_mfma_f32_16x16x32_bf16 v[28:31], v[148:151], v[196:199], v[28:31]
	v_mfma_f32_16x16x32_bf16 v[24:27], v[156:159], v[196:199], v[24:27]
	v_mfma_f32_16x16x32_bf16 v[12:15], v[148:151], v[204:207], v[12:15]
	v_mfma_f32_16x16x32_bf16 v[8:11], v[156:159], v[204:207], v[8:11]
	v_mfma_f32_16x16x32_bf16 v[52:55], v[160:163], v[176:179], v[52:55]
	v_mfma_f32_16x16x32_bf16 v[48:51], v[168:171], v[176:179], v[48:51]
	v_mfma_f32_16x16x32_bf16 v[36:39], v[160:163], v[184:187], v[36:39]
	v_mfma_f32_16x16x32_bf16 v[32:35], v[168:171], v[184:187], v[32:35]
	v_mfma_f32_16x16x32_bf16 v[20:23], v[160:163], v[192:195], v[20:23]
	v_mfma_f32_16x16x32_bf16 v[16:19], v[168:171], v[192:195], v[16:19]
	v_mfma_f32_16x16x32_bf16 v[4:7], v[160:163], v[200:203], v[4:7]
	v_mfma_f32_16x16x32_bf16 v[0:3], v[168:171], v[200:203], v[0:3]
	v_mfma_f32_16x16x32_bf16 v[52:55], v[164:167], v[180:183], v[52:55]
	v_mfma_f32_16x16x32_bf16 v[48:51], v[172:175], v[180:183], v[48:51]
	v_mfma_f32_16x16x32_bf16 v[36:39], v[164:167], v[188:191], v[36:39]
	v_mfma_f32_16x16x32_bf16 v[32:35], v[172:175], v[188:191], v[32:35]
	v_mfma_f32_16x16x32_bf16 v[20:23], v[164:167], v[196:199], v[20:23]
	v_mfma_f32_16x16x32_bf16 v[16:19], v[172:175], v[196:199], v[16:19]
	v_mfma_f32_16x16x32_bf16 v[4:7], v[164:167], v[204:207], v[4:7]
	v_mfma_f32_16x16x32_bf16 v[0:3], v[172:175], v[204:207], v[0:3]
	s_barrier
	s_add_i32 s35, s35, 2
	s_add_u32 s31, s31, 0x100
	s_addc_u32 s34, s34, 0
	s_cmpk_gt_u32 s35, 0x7d
	s_mov_b64 s[38:39], vcc
	s_cbranch_scc0 .LBB0_783
	s_and_b64 vcc, exec, s[96:97]
	s_cbranch_vccz .LBB0_786
	s_barrier
